# deferred_stats_atomics_p3_p6
# baseline (speedup 1.0000x reference)
; __device__ __forceinline__ unsigned pk2(float lo, float hi) { f32x2v v = {lo, hi}; b16x2v b = __builtin_convertvector(v, b16x2v); return __builtin_bit_cast(unsigned, b); }
; __device__ __forceinline__ float bflo(unsigned v) { return __uint_as_float(v << 16); }
; __device__ __forceinline__ float bfhi(unsigned v) { return __uint_as_float(v & 0xffff0000u); }
;     __device__ __forceinline__ void operator()(const f32x4 (&acc)[2][2][4][2], const Unit& u, int wr, int wc, int fr, int fq) const {
;     ...
;                 const int row = u.pm * 256 + ai * 128 + wr * 64 + m * 16 + fr;
;                 float mu = 0.f, rs = 1.f;
;                 if (MODE == 1) { const f32x2v s2 = *(const f32x2v*)(stp + 2 * row); mu = s2.x * (1.0f / DM); rs = rsqrtf(fmaxf(s2.y * (1.0f / DM) - mu * mu, 0.f) + LN_EPS); }
;                 const bf16_t* xrow = xb + (size_t)row * DM + colb; bf16_t* orow = Rb + (size_t)row * DM + colb;
;                 float sum = 0.f, sq = 0.f;
; #pragma unroll
;                 for (int bj = 0; bj < 2; ++bj) {
;                     const u32x4 xw = *(const u32x4*)(xrow + 128 * bj);
;                     f32x4 x0 = {bflo(xw.x), bfhi(xw.x), bflo(xw.y), bfhi(xw.y)}, x1 = {bflo(xw.z), bfhi(xw.z), bflo(xw.w), bfhi(xw.w)};
;                     if (MODE == 1) { x0 = (x0 - mu) * rs * g4[bj][0] + b4[bj][0]; x1 = (x1 - mu) * rs * g4[bj][1] + b4[bj][1]; }
;                     const f32x4 r0 = x0 * DN_ALPHA + acc[ai][bj][m][0], r1 = x1 * DN_ALPHA + acc[ai][bj][m][1];
;                     u32x4 w; w.x = pk2(r0[0], r0[1]); w.y = pk2(r0[2], r0[3]); w.z = pk2(r1[0], r1[1]); w.w = pk2(r1[2], r1[3]);
;                     *(u32x4*)(orow + 128 * bj) = w;
;                     sum += ((r0[0] + r0[1]) + (r0[2] + r0[3])) + ((r1[0] + r1[1]) + (r1[2] + r1[3]));
;                     sq += ((r0[0] * r0[0] + r0[1] * r0[1]) + (r0[2] * r0[2] + r0[3] * r0[3])) + ((r1[0] * r1[0] + r1[1] * r1[1]) + (r1[2] * r1[2] + r1[3] * r1[3]));
;                 }
;                 sum += __shfl_xor(sum, 16); sum += __shfl_xor(sum, 32); sq += __shfl_xor(sq, 16); sq += __shfl_xor(sq, 32);
;                 if (fq == 0) { atomicAdd(st + 2 * row, sum); atomicAdd(st + 2 * row + 1, sq); }
.LBB0_696:
	v_lshl_add_u32 v146, s28, 8, v155
	v_lshl_or_b32 v144, s30, 8, v157
	v_ashrrev_i32_e32 v147, 31, v146
	v_ashrrev_i32_e32 v145, 31, v144
	v_lshlrev_b64 v[172:173], 11, v[146:147]
	v_lshl_add_u64 v[162:163], s[0:1], 0, v[172:173]
	v_lshlrev_b64 v[144:145], 1, v[144:145]
	v_lshl_add_u64 v[162:163], v[162:163], 0, v[144:145]
	global_load_dwordx4 v[164:167], v[162:163], off
	global_load_dwordx4 v[168:171], v[162:163], off offset:256
	v_and_b32_e32 v162, 64, v161
	v_xor_b32_e32 v147, 16, v161
	v_add_u32_e32 v162, 64, v162
	v_xor_b32_e32 v163, 32, v161
	v_cmp_lt_i32_e32 vcc, v147, v162
	v_lshl_add_u64 v[172:173], s[6:7], 0, v[172:173]
	v_lshl_add_u64 v[172:173], v[172:173], 0, v[144:145]
	v_cndmask_b32_e32 v147, v161, v147, vcc
	v_cmp_lt_i32_e32 vcc, v163, v162
	v_lshlrev_b32_e32 v162, 2, v147
	s_waitcnt vmcnt(0)
	v_lshlrev_b32_e32 v174, 16, v164
	v_and_b32_e32 v175, 0xffff0000, v164
	v_lshlrev_b32_e32 v164, 16, v165
	v_and_b32_e32 v165, 0xffff0000, v165
	v_lshlrev_b32_e32 v176, 16, v166
	v_and_b32_e32 v177, 0xffff0000, v166
	v_lshlrev_b32_e32 v166, 16, v167
	v_and_b32_e32 v167, 0xffff0000, v167
	v_lshlrev_b32_e32 v178, 16, v168
	v_and_b32_e32 v179, 0xffff0000, v168
	v_lshlrev_b32_e32 v168, 16, v169
	v_and_b32_e32 v169, 0xffff0000, v169
	v_lshlrev_b32_e32 v180, 16, v170
	v_and_b32_e32 v181, 0xffff0000, v170
	v_lshlrev_b32_e32 v170, 16, v171
	v_and_b32_e32 v171, 0xffff0000, v171
	v_cndmask_b32_e32 v163, v161, v163, vcc
	v_pk_fma_f32 v[126:127], v[164:165], s[18:19], v[126:127] op_sel_hi:[1,0,1]
	v_pk_fma_f32 v[124:125], v[174:175], s[18:19], v[124:125] op_sel_hi:[1,0,1]
	v_pk_fma_f32 v[122:123], v[166:167], s[18:19], v[122:123] op_sel_hi:[1,0,1]
	v_pk_fma_f32 v[120:121], v[176:177], s[18:19], v[120:121] op_sel_hi:[1,0,1]
	v_pk_fma_f32 v[118:119], v[168:169], s[18:19], v[118:119] op_sel_hi:[1,0,1]
	v_pk_fma_f32 v[116:117], v[178:179], s[18:19], v[116:117] op_sel_hi:[1,0,1]
	v_pk_fma_f32 v[164:165], v[170:171], s[18:19], v[114:115] op_sel_hi:[1,0,1]
	v_pk_fma_f32 v[166:167], v[180:181], s[18:19], v[112:113] op_sel_hi:[1,0,1]
	v_lshlrev_b32_e32 v147, 2, v163
	v_cvt_pk_bf16_f32 v112, v124, v125
	v_cvt_pk_bf16_f32 v113, v126, v127
	v_cvt_pk_bf16_f32 v114, v120, v121
	v_add_f32_e32 v115, v124, v125
	v_add_f32_e32 v163, v126, v127
	v_add_f32_e32 v168, v120, v121
	v_add_f32_e32 v169, v122, v123
	v_mul_f32_e32 v125, v125, v125
	v_mul_f32_e32 v127, v127, v127
	v_mul_f32_e32 v121, v121, v121
	v_mul_f32_e32 v170, v123, v123
	v_add_f32_e32 v171, v116, v117
	v_add_f32_e32 v174, v118, v119
	v_add_f32_e32 v175, v166, v167
	v_add_f32_e32 v176, v164, v165
	v_mul_f32_e32 v177, v117, v117
	v_mul_f32_e32 v178, v119, v119
	v_mul_f32_e32 v179, v167, v167
	v_mul_f32_e32 v180, v165, v165
	v_add_f32_e32 v115, v115, v163
	v_add_f32_e32 v163, v168, v169
	v_fmac_f32_e32 v125, v124, v124
	v_fmac_f32_e32 v127, v126, v126
	v_fmac_f32_e32 v121, v120, v120
	v_fmac_f32_e32 v170, v122, v122
	v_add_f32_e32 v120, v171, v174
	v_add_f32_e32 v124, v175, v176
	v_fmac_f32_e32 v177, v116, v116
	v_fmac_f32_e32 v178, v118, v118
	v_fmac_f32_e32 v179, v166, v166
	v_fmac_f32_e32 v180, v164, v164
	v_add_f32_e32 v115, v115, v163
	v_add_f32_e32 v125, v125, v127
	v_add_f32_e32 v121, v121, v170
	v_add_f32_e32 v120, v120, v124
	v_add_f32_e32 v124, v177, v178
	v_add_f32_e32 v126, v179, v180
	v_add_f32_e32 v115, 0, v115
	v_add_f32_e32 v121, v125, v121
	v_add_f32_e32 v124, v124, v126
	v_add_f32_e32 v120, v115, v120
	v_add_f32_e32 v121, v121, v124
	ds_bpermute_b32 v124, v162, v120
	ds_bpermute_b32 v125, v162, v121
	v_cvt_pk_bf16_f32 v115, v122, v123
	global_store_dwordx4 v[172:173], v[112:115], off
	v_cvt_pk_bf16_f32 v116, v116, v117
	v_cvt_pk_bf16_f32 v117, v118, v119
	s_waitcnt lgkmcnt(1)
	v_add_f32_e32 v112, v120, v124
	s_waitcnt lgkmcnt(0)
	v_add_f32_e32 v113, v121, v125
	ds_bpermute_b32 v114, v147, v112
	ds_bpermute_b32 v115, v147, v113
	v_cvt_pk_bf16_f32 v118, v166, v167
	v_cvt_pk_bf16_f32 v119, v164, v165
	global_store_dwordx4 v[172:173], v[116:119], off offset:256
	s_and_saveexec_b64 s[28:29], s[2:3]
	s_cbranch_execz .LBB0_698
	v_lshlrev_b32_e32 v116, 1, v146
	v_ashrrev_i32_e32 v117, 31, v116
	v_lshl_add_u64 v[116:117], v[116:117], 2, s[58:59]
	s_waitcnt lgkmcnt(1)
	v_add_f32_e32 v112, v112, v114
	s_waitcnt lgkmcnt(0)
	v_add_f32_e32 v113, v113, v115
	v_mov_b32_e32 v194, v112
	v_mov_b32_e32 v195, v113
; __device__ __forceinline__ unsigned pk2(float lo, float hi) { f32x2v v = {lo, hi}; b16x2v b = __builtin_convertvector(v, b16x2v); return __builtin_bit_cast(unsigned, b); }
; __device__ __forceinline__ float bflo(unsigned v) { return __uint_as_float(v << 16); }
; __device__ __forceinline__ float bfhi(unsigned v) { return __uint_as_float(v & 0xffff0000u); }
;     __device__ __forceinline__ void operator()(const f32x4 (&acc)[2][2][4][2], const Unit& u, int wr, int wc, int fr, int fq) const {
;     ...
;                 const int row = u.pm * 256 + ai * 128 + wr * 64 + m * 16 + fr;
;                 float mu = 0.f, rs = 1.f;
;                 if (MODE == 1) { const f32x2v s2 = *(const f32x2v*)(stp + 2 * row); mu = s2.x * (1.0f / DM); rs = rsqrtf(fmaxf(s2.y * (1.0f / DM) - mu * mu, 0.f) + LN_EPS); }
;                 const bf16_t* xrow = xb + (size_t)row * DM + colb; bf16_t* orow = Rb + (size_t)row * DM + colb;
;                 float sum = 0.f, sq = 0.f;
; #pragma unroll
;                 for (int bj = 0; bj < 2; ++bj) {
;                     const u32x4 xw = *(const u32x4*)(xrow + 128 * bj);
;                     f32x4 x0 = {bflo(xw.x), bfhi(xw.x), bflo(xw.y), bfhi(xw.y)}, x1 = {bflo(xw.z), bfhi(xw.z), bflo(xw.w), bfhi(xw.w)};
;                     if (MODE == 1) { x0 = (x0 - mu) * rs * g4[bj][0] + b4[bj][0]; x1 = (x1 - mu) * rs * g4[bj][1] + b4[bj][1]; }
;                     const f32x4 r0 = x0 * DN_ALPHA + acc[ai][bj][m][0], r1 = x1 * DN_ALPHA + acc[ai][bj][m][1];
;                     u32x4 w; w.x = pk2(r0[0], r0[1]); w.y = pk2(r0[2], r0[3]); w.z = pk2(r1[0], r1[1]); w.w = pk2(r1[2], r1[3]);
;                     *(u32x4*)(orow + 128 * bj) = w;
;                     sum += ((r0[0] + r0[1]) + (r0[2] + r0[3])) + ((r1[0] + r1[1]) + (r1[2] + r1[3]));
;                     sq += ((r0[0] * r0[0] + r0[1] * r0[1]) + (r0[2] * r0[2] + r0[3] * r0[3])) + ((r1[0] * r1[0] + r1[1] * r1[1]) + (r1[2] * r1[2] + r1[3] * r1[3]));
;                 }
;                 sum += __shfl_xor(sum, 16); sum += __shfl_xor(sum, 32); sq += __shfl_xor(sq, 16); sq += __shfl_xor(sq, 32);
;                 if (fq == 0) { atomicAdd(st + 2 * row, sum); atomicAdd(st + 2 * row + 1, sq); }
.LBB0_698:
	s_or_b64 exec, exec, s[28:29]
	v_or_b32_e32 v112, 16, v146
	v_ashrrev_i32_e32 v113, 31, v112
	v_lshlrev_b64 v[122:123], 11, v[112:113]
	s_waitcnt lgkmcnt(0)
	v_lshl_add_u64 v[114:115], s[0:1], 0, v[122:123]
	v_lshl_add_u64 v[118:119], v[114:115], 0, v[144:145]
	global_load_dwordx4 v[114:117], v[118:119], off
	s_nop 0
	global_load_dwordx4 v[118:121], v[118:119], off offset:256
	v_lshl_add_u64 v[122:123], s[6:7], 0, v[122:123]
	v_lshl_add_u64 v[122:123], v[122:123], 0, v[144:145]
	s_waitcnt vmcnt(1)
	v_lshlrev_b32_e32 v124, 16, v114
	v_and_b32_e32 v125, 0xffff0000, v114
	v_lshlrev_b32_e32 v114, 16, v115
	v_and_b32_e32 v115, 0xffff0000, v115
	v_lshlrev_b32_e32 v126, 16, v116
	v_and_b32_e32 v127, 0xffff0000, v116
	v_lshlrev_b32_e32 v116, 16, v117
	v_and_b32_e32 v117, 0xffff0000, v117
	s_waitcnt vmcnt(0)
	v_lshlrev_b32_e32 v164, 16, v118
	v_and_b32_e32 v165, 0xffff0000, v118
	v_lshlrev_b32_e32 v118, 16, v119
	v_and_b32_e32 v119, 0xffff0000, v119
	v_lshlrev_b32_e32 v166, 16, v120
	v_and_b32_e32 v167, 0xffff0000, v120
	v_lshlrev_b32_e32 v120, 16, v121
	v_and_b32_e32 v121, 0xffff0000, v121
	v_pk_fma_f32 v[110:111], v[114:115], s[18:19], v[110:111] op_sel_hi:[1,0,1]
	v_pk_fma_f32 v[108:109], v[124:125], s[18:19], v[108:109] op_sel_hi:[1,0,1]
	v_pk_fma_f32 v[106:107], v[116:117], s[18:19], v[106:107] op_sel_hi:[1,0,1]
	v_pk_fma_f32 v[104:105], v[126:127], s[18:19], v[104:105] op_sel_hi:[1,0,1]
	v_pk_fma_f32 v[102:103], v[118:119], s[18:19], v[102:103] op_sel_hi:[1,0,1]
	v_pk_fma_f32 v[100:101], v[164:165], s[18:19], v[100:101] op_sel_hi:[1,0,1]
	v_pk_fma_f32 v[114:115], v[120:121], s[18:19], v[98:99] op_sel_hi:[1,0,1]
	v_pk_fma_f32 v[116:117], v[166:167], s[18:19], v[96:97] op_sel_hi:[1,0,1]
	v_cvt_pk_bf16_f32 v96, v108, v109
	v_cvt_pk_bf16_f32 v97, v110, v111
	v_cvt_pk_bf16_f32 v98, v104, v105
	v_add_f32_e32 v99, v108, v109
	v_add_f32_e32 v113, v110, v111
	v_add_f32_e32 v118, v104, v105
	v_add_f32_e32 v119, v106, v107
	v_mul_f32_e32 v109, v109, v109
	v_mul_f32_e32 v111, v111, v111
	v_mul_f32_e32 v105, v105, v105
	v_mul_f32_e32 v120, v107, v107
	v_add_f32_e32 v121, v100, v101
	v_add_f32_e32 v124, v102, v103
	v_add_f32_e32 v125, v116, v117
	v_add_f32_e32 v126, v114, v115
	v_mul_f32_e32 v127, v101, v101
	v_mul_f32_e32 v163, v103, v103
	v_mul_f32_e32 v164, v117, v117
	v_mul_f32_e32 v165, v115, v115
	v_add_f32_e32 v99, v99, v113
	v_add_f32_e32 v113, v118, v119
	v_fmac_f32_e32 v109, v108, v108
	v_fmac_f32_e32 v111, v110, v110
	v_fmac_f32_e32 v105, v104, v104
	v_fmac_f32_e32 v120, v106, v106
	v_add_f32_e32 v104, v121, v124
	v_add_f32_e32 v108, v125, v126
	v_fmac_f32_e32 v127, v100, v100
	v_fmac_f32_e32 v163, v102, v102
	v_fmac_f32_e32 v164, v116, v116
	v_fmac_f32_e32 v165, v114, v114
	v_add_f32_e32 v99, v99, v113
	v_add_f32_e32 v109, v109, v111
	v_add_f32_e32 v105, v105, v120
	v_add_f32_e32 v104, v104, v108
	v_add_f32_e32 v108, v127, v163
	v_add_f32_e32 v110, v164, v165
	v_add_f32_e32 v99, 0, v99
	v_add_f32_e32 v105, v109, v105
	v_add_f32_e32 v108, v108, v110
	v_add_f32_e32 v104, v99, v104
	v_add_f32_e32 v105, v105, v108
	ds_bpermute_b32 v108, v162, v104
	ds_bpermute_b32 v109, v162, v105
	v_cvt_pk_bf16_f32 v99, v106, v107
	global_store_dwordx4 v[122:123], v[96:99], off
	v_cvt_pk_bf16_f32 v100, v100, v101
	v_cvt_pk_bf16_f32 v101, v102, v103
	s_waitcnt lgkmcnt(1)
	v_add_f32_e32 v96, v104, v108
	s_waitcnt lgkmcnt(0)
	v_add_f32_e32 v97, v105, v109
	ds_bpermute_b32 v98, v147, v96
	ds_bpermute_b32 v99, v147, v97
	v_cvt_pk_bf16_f32 v102, v116, v117
	v_cvt_pk_bf16_f32 v103, v114, v115
	global_store_dwordx4 v[122:123], v[100:103], off offset:256
	s_and_saveexec_b64 s[28:29], s[2:3]
	s_cbranch_execz .LBB0_700
	v_lshlrev_b32_e32 v100, 1, v112
	v_ashrrev_i32_e32 v101, 31, v100
	v_lshl_add_u64 v[100:101], v[100:101], 2, s[58:59]
	s_waitcnt lgkmcnt(1)
	v_add_f32_e32 v96, v96, v98
	s_waitcnt lgkmcnt(0)
	v_add_f32_e32 v97, v97, v99
	v_mov_b32_e32 v196, v96
	v_mov_b32_e32 v197, v97
.LBB0_700:
	s_or_b64 exec, exec, s[28:29]
	v_or_b32_e32 v96, 32, v146
	v_ashrrev_i32_e32 v97, 31, v96
	v_lshlrev_b64 v[106:107], 11, v[96:97]
	s_waitcnt lgkmcnt(0)
	v_lshl_add_u64 v[98:99], s[0:1], 0, v[106:107]
	v_lshl_add_u64 v[102:103], v[98:99], 0, v[144:145]
	global_load_dwordx4 v[98:101], v[102:103], off
	s_nop 0
	global_load_dwordx4 v[102:105], v[102:103], off offset:256
	v_lshl_add_u64 v[106:107], s[6:7], 0, v[106:107]
	v_lshl_add_u64 v[106:107], v[106:107], 0, v[144:145]
	s_waitcnt vmcnt(1)
	v_lshlrev_b32_e32 v108, 16, v98
	v_and_b32_e32 v109, 0xffff0000, v98
	v_lshlrev_b32_e32 v98, 16, v99
	v_and_b32_e32 v99, 0xffff0000, v99
	v_lshlrev_b32_e32 v110, 16, v100
	v_and_b32_e32 v111, 0xffff0000, v100
	v_lshlrev_b32_e32 v100, 16, v101
	v_and_b32_e32 v101, 0xffff0000, v101
	s_waitcnt vmcnt(0)
; __device__ __forceinline__ unsigned pk2(float lo, float hi) { f32x2v v = {lo, hi}; b16x2v b = __builtin_convertvector(v, b16x2v); return __builtin_bit_cast(unsigned, b); }
; __device__ __forceinline__ float bflo(unsigned v) { return __uint_as_float(v << 16); }
; __device__ __forceinline__ float bfhi(unsigned v) { return __uint_as_float(v & 0xffff0000u); }
;     __device__ __forceinline__ void operator()(const f32x4 (&acc)[2][2][4][2], const Unit& u, int wr, int wc, int fr, int fq) const {
;     ...
;                 const int row = u.pm * 256 + ai * 128 + wr * 64 + m * 16 + fr;
;                 float mu = 0.f, rs = 1.f;
;                 if (MODE == 1) { const f32x2v s2 = *(const f32x2v*)(stp + 2 * row); mu = s2.x * (1.0f / DM); rs = rsqrtf(fmaxf(s2.y * (1.0f / DM) - mu * mu, 0.f) + LN_EPS); }
;                 const bf16_t* xrow = xb + (size_t)row * DM + colb; bf16_t* orow = Rb + (size_t)row * DM + colb;
;                 float sum = 0.f, sq = 0.f;
; #pragma unroll
;                 for (int bj = 0; bj < 2; ++bj) {
;                     const u32x4 xw = *(const u32x4*)(xrow + 128 * bj);
;                     f32x4 x0 = {bflo(xw.x), bfhi(xw.x), bflo(xw.y), bfhi(xw.y)}, x1 = {bflo(xw.z), bfhi(xw.z), bflo(xw.w), bfhi(xw.w)};
;                     if (MODE == 1) { x0 = (x0 - mu) * rs * g4[bj][0] + b4[bj][0]; x1 = (x1 - mu) * rs * g4[bj][1] + b4[bj][1]; }
;                     const f32x4 r0 = x0 * DN_ALPHA + acc[ai][bj][m][0], r1 = x1 * DN_ALPHA + acc[ai][bj][m][1];
;                     u32x4 w; w.x = pk2(r0[0], r0[1]); w.y = pk2(r0[2], r0[3]); w.z = pk2(r1[0], r1[1]); w.w = pk2(r1[2], r1[3]);
;                     *(u32x4*)(orow + 128 * bj) = w;
;                     sum += ((r0[0] + r0[1]) + (r0[2] + r0[3])) + ((r1[0] + r1[1]) + (r1[2] + r1[3]));
;                     sq += ((r0[0] * r0[0] + r0[1] * r0[1]) + (r0[2] * r0[2] + r0[3] * r0[3])) + ((r1[0] * r1[0] + r1[1] * r1[1]) + (r1[2] * r1[2] + r1[3] * r1[3]));
;                 }
;                 sum += __shfl_xor(sum, 16); sum += __shfl_xor(sum, 32); sq += __shfl_xor(sq, 16); sq += __shfl_xor(sq, 32);
;                 if (fq == 0) { atomicAdd(st + 2 * row, sum); atomicAdd(st + 2 * row + 1, sq); }
	v_lshlrev_b32_e32 v112, 16, v102
	v_and_b32_e32 v113, 0xffff0000, v102
	v_lshlrev_b32_e32 v102, 16, v103
	v_and_b32_e32 v103, 0xffff0000, v103
	v_lshlrev_b32_e32 v114, 16, v104
	v_and_b32_e32 v115, 0xffff0000, v104
	v_lshlrev_b32_e32 v104, 16, v105
	v_and_b32_e32 v105, 0xffff0000, v105
	v_pk_fma_f32 v[94:95], v[98:99], s[18:19], v[94:95] op_sel_hi:[1,0,1]
	v_pk_fma_f32 v[92:93], v[108:109], s[18:19], v[92:93] op_sel_hi:[1,0,1]
	v_pk_fma_f32 v[90:91], v[100:101], s[18:19], v[90:91] op_sel_hi:[1,0,1]
	v_pk_fma_f32 v[88:89], v[110:111], s[18:19], v[88:89] op_sel_hi:[1,0,1]
	v_pk_fma_f32 v[86:87], v[102:103], s[18:19], v[86:87] op_sel_hi:[1,0,1]
	v_pk_fma_f32 v[84:85], v[112:113], s[18:19], v[84:85] op_sel_hi:[1,0,1]
	v_pk_fma_f32 v[98:99], v[104:105], s[18:19], v[82:83] op_sel_hi:[1,0,1]
	v_pk_fma_f32 v[100:101], v[114:115], s[18:19], v[80:81] op_sel_hi:[1,0,1]
	v_cvt_pk_bf16_f32 v80, v92, v93
	v_cvt_pk_bf16_f32 v81, v94, v95
	v_cvt_pk_bf16_f32 v82, v88, v89
	v_add_f32_e32 v83, v92, v93
	v_add_f32_e32 v97, v94, v95
	v_add_f32_e32 v102, v88, v89
	v_add_f32_e32 v103, v90, v91
	v_mul_f32_e32 v93, v93, v93
	v_mul_f32_e32 v95, v95, v95
	v_mul_f32_e32 v89, v89, v89
	v_mul_f32_e32 v104, v91, v91
	v_add_f32_e32 v105, v84, v85
	v_add_f32_e32 v108, v86, v87
	v_add_f32_e32 v109, v100, v101
	v_add_f32_e32 v110, v98, v99
	v_mul_f32_e32 v111, v85, v85
	v_mul_f32_e32 v112, v87, v87
	v_mul_f32_e32 v113, v101, v101
	v_mul_f32_e32 v114, v99, v99
	v_add_f32_e32 v83, v83, v97
	v_add_f32_e32 v97, v102, v103
	v_fmac_f32_e32 v93, v92, v92
	v_fmac_f32_e32 v95, v94, v94
	v_fmac_f32_e32 v89, v88, v88
	v_fmac_f32_e32 v104, v90, v90
	v_add_f32_e32 v88, v105, v108
	v_add_f32_e32 v92, v109, v110
	v_fmac_f32_e32 v111, v84, v84
	v_fmac_f32_e32 v112, v86, v86
	v_fmac_f32_e32 v113, v100, v100
	v_fmac_f32_e32 v114, v98, v98
	v_add_f32_e32 v83, v83, v97
	v_add_f32_e32 v93, v93, v95
	v_add_f32_e32 v89, v89, v104
	v_add_f32_e32 v88, v88, v92
	v_add_f32_e32 v92, v111, v112
	v_add_f32_e32 v94, v113, v114
	v_add_f32_e32 v83, 0, v83
	v_add_f32_e32 v89, v93, v89
	v_add_f32_e32 v92, v92, v94
	v_add_f32_e32 v88, v83, v88
	v_add_f32_e32 v89, v89, v92
	ds_bpermute_b32 v92, v162, v88
	ds_bpermute_b32 v93, v162, v89
	v_cvt_pk_bf16_f32 v83, v90, v91
	global_store_dwordx4 v[106:107], v[80:83], off
	v_cvt_pk_bf16_f32 v84, v84, v85
	v_cvt_pk_bf16_f32 v85, v86, v87
	s_waitcnt lgkmcnt(1)
	v_add_f32_e32 v80, v88, v92
	s_waitcnt lgkmcnt(0)
	v_add_f32_e32 v81, v89, v93
	ds_bpermute_b32 v82, v147, v80
	ds_bpermute_b32 v83, v147, v81
	v_cvt_pk_bf16_f32 v86, v100, v101
	v_cvt_pk_bf16_f32 v87, v98, v99
	global_store_dwordx4 v[106:107], v[84:87], off offset:256
	s_and_saveexec_b64 s[28:29], s[2:3]
	s_cbranch_execz .LBB0_702
	v_lshlrev_b32_e32 v84, 1, v96
	v_ashrrev_i32_e32 v85, 31, v84
	v_lshl_add_u64 v[84:85], v[84:85], 2, s[58:59]
	s_waitcnt lgkmcnt(1)
	v_add_f32_e32 v80, v80, v82
	s_waitcnt lgkmcnt(0)
	v_add_f32_e32 v81, v81, v83
	v_mov_b32_e32 v198, v80
	v_mov_b32_e32 v199, v81
.LBB0_702:
	s_or_b64 exec, exec, s[28:29]
	v_or_b32_e32 v80, 48, v146
	v_ashrrev_i32_e32 v81, 31, v80
	v_lshlrev_b64 v[90:91], 11, v[80:81]
	s_waitcnt lgkmcnt(0)
	v_lshl_add_u64 v[82:83], s[0:1], 0, v[90:91]
	v_lshl_add_u64 v[86:87], v[82:83], 0, v[144:145]
	global_load_dwordx4 v[82:85], v[86:87], off
	s_nop 0
	global_load_dwordx4 v[86:89], v[86:87], off offset:256
	v_lshl_add_u64 v[90:91], s[6:7], 0, v[90:91]
	v_lshl_add_u64 v[90:91], v[90:91], 0, v[144:145]
	s_waitcnt vmcnt(1)
	v_lshlrev_b32_e32 v92, 16, v82
	v_and_b32_e32 v93, 0xffff0000, v82
	v_lshlrev_b32_e32 v82, 16, v83
	v_and_b32_e32 v83, 0xffff0000, v83
	v_lshlrev_b32_e32 v94, 16, v84
	v_and_b32_e32 v95, 0xffff0000, v84
	v_lshlrev_b32_e32 v84, 16, v85
	v_and_b32_e32 v85, 0xffff0000, v85
	s_waitcnt vmcnt(0)
	v_lshlrev_b32_e32 v96, 16, v86
	v_and_b32_e32 v97, 0xffff0000, v86
	v_lshlrev_b32_e32 v86, 16, v87
	v_and_b32_e32 v87, 0xffff0000, v87
	v_lshlrev_b32_e32 v98, 16, v88
	v_and_b32_e32 v99, 0xffff0000, v88
	v_lshlrev_b32_e32 v88, 16, v89
	v_and_b32_e32 v89, 0xffff0000, v89
	v_pk_fma_f32 v[78:79], v[82:83], s[18:19], v[78:79] op_sel_hi:[1,0,1]
	v_pk_fma_f32 v[76:77], v[92:93], s[18:19], v[76:77] op_sel_hi:[1,0,1]
	v_pk_fma_f32 v[74:75], v[84:85], s[18:19], v[74:75] op_sel_hi:[1,0,1]
	v_pk_fma_f32 v[72:73], v[94:95], s[18:19], v[72:73] op_sel_hi:[1,0,1]
	v_pk_fma_f32 v[70:71], v[86:87], s[18:19], v[70:71] op_sel_hi:[1,0,1]
	v_pk_fma_f32 v[68:69], v[96:97], s[18:19], v[68:69] op_sel_hi:[1,0,1]
	v_pk_fma_f32 v[82:83], v[88:89], s[18:19], v[66:67] op_sel_hi:[1,0,1]
	v_pk_fma_f32 v[84:85], v[98:99], s[18:19], v[64:65] op_sel_hi:[1,0,1]
	v_cvt_pk_bf16_f32 v64, v76, v77
	v_cvt_pk_bf16_f32 v65, v78, v79
	v_cvt_pk_bf16_f32 v66, v72, v73
	v_add_f32_e32 v67, v76, v77
	v_add_f32_e32 v81, v78, v79
	v_add_f32_e32 v86, v72, v73
	v_add_f32_e32 v87, v74, v75
	v_mul_f32_e32 v77, v77, v77
	v_mul_f32_e32 v79, v79, v79
	v_mul_f32_e32 v73, v73, v73
	v_mul_f32_e32 v88, v75, v75
	v_add_f32_e32 v89, v68, v69
	v_add_f32_e32 v92, v70, v71
	v_add_f32_e32 v93, v84, v85
	v_add_f32_e32 v94, v82, v83
	v_mul_f32_e32 v95, v69, v69
	v_mul_f32_e32 v96, v71, v71
	v_mul_f32_e32 v97, v85, v85
	v_mul_f32_e32 v98, v83, v83
	v_add_f32_e32 v67, v67, v81
	v_add_f32_e32 v81, v86, v87
	v_fmac_f32_e32 v77, v76, v76
	v_fmac_f32_e32 v79, v78, v78
	v_fmac_f32_e32 v73, v72, v72
	v_fmac_f32_e32 v88, v74, v74
	v_add_f32_e32 v72, v89, v92
	v_add_f32_e32 v76, v93, v94
	v_fmac_f32_e32 v95, v68, v68
	v_fmac_f32_e32 v96, v70, v70
	v_fmac_f32_e32 v97, v84, v84
	v_fmac_f32_e32 v98, v82, v82
	v_add_f32_e32 v67, v67, v81
	v_add_f32_e32 v77, v77, v79
	v_add_f32_e32 v73, v73, v88
	v_add_f32_e32 v72, v72, v76
	v_add_f32_e32 v76, v95, v96
	v_add_f32_e32 v78, v97, v98
	v_add_f32_e32 v67, 0, v67
	v_add_f32_e32 v73, v77, v73
	v_add_f32_e32 v76, v76, v78
	v_add_f32_e32 v72, v67, v72
	v_add_f32_e32 v73, v73, v76
	ds_bpermute_b32 v76, v162, v72
	ds_bpermute_b32 v77, v162, v73
	v_cvt_pk_bf16_f32 v67, v74, v75
	global_store_dwordx4 v[90:91], v[64:67], off
	v_cvt_pk_bf16_f32 v68, v68, v69
	v_cvt_pk_bf16_f32 v69, v70, v71
	s_waitcnt lgkmcnt(1)
	v_add_f32_e32 v64, v72, v76
	s_waitcnt lgkmcnt(0)
	v_add_f32_e32 v65, v73, v77
	ds_bpermute_b32 v66, v147, v64
	ds_bpermute_b32 v67, v147, v65
	v_cvt_pk_bf16_f32 v70, v84, v85
	v_cvt_pk_bf16_f32 v71, v82, v83
	global_store_dwordx4 v[90:91], v[68:71], off offset:256
	s_and_saveexec_b64 s[28:29], s[2:3]
	s_cbranch_execz .LBB0_704
	v_lshlrev_b32_e32 v68, 1, v80
	v_ashrrev_i32_e32 v69, 31, v68
	v_lshl_add_u64 v[68:69], v[68:69], 2, s[58:59]
	s_waitcnt lgkmcnt(1)
	v_add_f32_e32 v64, v64, v66
	s_waitcnt lgkmcnt(0)
	v_add_f32_e32 v65, v65, v67
	v_mov_b32_e32 v200, v64
	v_mov_b32_e32 v201, v65
; __device__ __forceinline__ unsigned pk2(float lo, float hi) { f32x2v v = {lo, hi}; b16x2v b = __builtin_convertvector(v, b16x2v); return __builtin_bit_cast(unsigned, b); }
; __device__ __forceinline__ float bflo(unsigned v) { return __uint_as_float(v << 16); }
; __device__ __forceinline__ float bfhi(unsigned v) { return __uint_as_float(v & 0xffff0000u); }
;     __device__ __forceinline__ void operator()(const f32x4 (&acc)[2][2][4][2], const Unit& u, int wr, int wc, int fr, int fq) const {
;     ...
;                 const int row = u.pm * 256 + ai * 128 + wr * 64 + m * 16 + fr;
;                 float mu = 0.f, rs = 1.f;
;                 if (MODE == 1) { const f32x2v s2 = *(const f32x2v*)(stp + 2 * row); mu = s2.x * (1.0f / DM); rs = rsqrtf(fmaxf(s2.y * (1.0f / DM) - mu * mu, 0.f) + LN_EPS); }
;                 const bf16_t* xrow = xb + (size_t)row * DM + colb; bf16_t* orow = Rb + (size_t)row * DM + colb;
;                 float sum = 0.f, sq = 0.f;
; #pragma unroll
;                 for (int bj = 0; bj < 2; ++bj) {
;                     const u32x4 xw = *(const u32x4*)(xrow + 128 * bj);
;                     f32x4 x0 = {bflo(xw.x), bfhi(xw.x), bflo(xw.y), bfhi(xw.y)}, x1 = {bflo(xw.z), bfhi(xw.z), bflo(xw.w), bfhi(xw.w)};
;                     if (MODE == 1) { x0 = (x0 - mu) * rs * g4[bj][0] + b4[bj][0]; x1 = (x1 - mu) * rs * g4[bj][1] + b4[bj][1]; }
;                     const f32x4 r0 = x0 * DN_ALPHA + acc[ai][bj][m][0], r1 = x1 * DN_ALPHA + acc[ai][bj][m][1];
;                     u32x4 w; w.x = pk2(r0[0], r0[1]); w.y = pk2(r0[2], r0[3]); w.z = pk2(r1[0], r1[1]); w.w = pk2(r1[2], r1[3]);
;                     *(u32x4*)(orow + 128 * bj) = w;
;                     sum += ((r0[0] + r0[1]) + (r0[2] + r0[3])) + ((r1[0] + r1[1]) + (r1[2] + r1[3]));
;                     sq += ((r0[0] * r0[0] + r0[1] * r0[1]) + (r0[2] * r0[2] + r0[3] * r0[3])) + ((r1[0] * r1[0] + r1[1] * r1[1]) + (r1[2] * r1[2] + r1[3] * r1[3]));
;                 }
;                 sum += __shfl_xor(sum, 16); sum += __shfl_xor(sum, 32); sq += __shfl_xor(sq, 16); sq += __shfl_xor(sq, 32);
;                 if (fq == 0) { atomicAdd(st + 2 * row, sum); atomicAdd(st + 2 * row + 1, sq); }
.LBB0_704:
	s_or_b64 exec, exec, s[28:29]
	v_add_u32_e32 v64, 0x80, v146
	v_ashrrev_i32_e32 v65, 31, v64
	v_lshlrev_b64 v[74:75], 11, v[64:65]
	s_waitcnt lgkmcnt(0)
	v_lshl_add_u64 v[66:67], s[0:1], 0, v[74:75]
	v_lshl_add_u64 v[70:71], v[66:67], 0, v[144:145]
	global_load_dwordx4 v[66:69], v[70:71], off
	s_nop 0
	global_load_dwordx4 v[70:73], v[70:71], off offset:256
	v_lshl_add_u64 v[74:75], s[6:7], 0, v[74:75]
	v_lshl_add_u64 v[74:75], v[74:75], 0, v[144:145]
	s_waitcnt vmcnt(1)
	v_lshlrev_b32_e32 v76, 16, v66
	v_and_b32_e32 v77, 0xffff0000, v66
	v_lshlrev_b32_e32 v66, 16, v67
	v_and_b32_e32 v67, 0xffff0000, v67
	v_lshlrev_b32_e32 v78, 16, v68
	v_and_b32_e32 v79, 0xffff0000, v68
	v_lshlrev_b32_e32 v68, 16, v69
	v_and_b32_e32 v69, 0xffff0000, v69
	s_waitcnt vmcnt(0)
	v_lshlrev_b32_e32 v80, 16, v70
	v_and_b32_e32 v81, 0xffff0000, v70
	v_lshlrev_b32_e32 v70, 16, v71
	v_and_b32_e32 v71, 0xffff0000, v71
	v_lshlrev_b32_e32 v82, 16, v72
	v_and_b32_e32 v83, 0xffff0000, v72
	v_lshlrev_b32_e32 v72, 16, v73
	v_and_b32_e32 v73, 0xffff0000, v73
	v_pk_fma_f32 v[62:63], v[66:67], s[18:19], v[62:63] op_sel_hi:[1,0,1]
	v_pk_fma_f32 v[60:61], v[76:77], s[18:19], v[60:61] op_sel_hi:[1,0,1]
	v_pk_fma_f32 v[58:59], v[68:69], s[18:19], v[58:59] op_sel_hi:[1,0,1]
	v_pk_fma_f32 v[56:57], v[78:79], s[18:19], v[56:57] op_sel_hi:[1,0,1]
	v_pk_fma_f32 v[54:55], v[70:71], s[18:19], v[54:55] op_sel_hi:[1,0,1]
	v_pk_fma_f32 v[52:53], v[80:81], s[18:19], v[52:53] op_sel_hi:[1,0,1]
	v_pk_fma_f32 v[66:67], v[72:73], s[18:19], v[50:51] op_sel_hi:[1,0,1]
	v_pk_fma_f32 v[68:69], v[82:83], s[18:19], v[48:49] op_sel_hi:[1,0,1]
	v_cvt_pk_bf16_f32 v48, v60, v61
	v_cvt_pk_bf16_f32 v49, v62, v63
	v_cvt_pk_bf16_f32 v50, v56, v57
	v_add_f32_e32 v51, v60, v61
	v_add_f32_e32 v65, v62, v63
	v_add_f32_e32 v70, v56, v57
	v_add_f32_e32 v71, v58, v59
	v_mul_f32_e32 v61, v61, v61
	v_mul_f32_e32 v63, v63, v63
	v_mul_f32_e32 v57, v57, v57
	v_mul_f32_e32 v72, v59, v59
	v_add_f32_e32 v73, v52, v53
	v_add_f32_e32 v76, v54, v55
	v_add_f32_e32 v77, v68, v69
	v_add_f32_e32 v78, v66, v67
	v_mul_f32_e32 v79, v53, v53
	v_mul_f32_e32 v80, v55, v55
	v_mul_f32_e32 v81, v69, v69
	v_mul_f32_e32 v82, v67, v67
	v_add_f32_e32 v51, v51, v65
	v_add_f32_e32 v65, v70, v71
	v_fmac_f32_e32 v61, v60, v60
	v_fmac_f32_e32 v63, v62, v62
	v_fmac_f32_e32 v57, v56, v56
	v_fmac_f32_e32 v72, v58, v58
	v_add_f32_e32 v56, v73, v76
	v_add_f32_e32 v60, v77, v78
	v_fmac_f32_e32 v79, v52, v52
	v_fmac_f32_e32 v80, v54, v54
	v_fmac_f32_e32 v81, v68, v68
	v_fmac_f32_e32 v82, v66, v66
	v_add_f32_e32 v51, v51, v65
	v_add_f32_e32 v61, v61, v63
	v_add_f32_e32 v57, v57, v72
	v_add_f32_e32 v56, v56, v60
	v_add_f32_e32 v60, v79, v80
	v_add_f32_e32 v62, v81, v82
	v_add_f32_e32 v51, 0, v51
	v_add_f32_e32 v57, v61, v57
	v_add_f32_e32 v60, v60, v62
	v_add_f32_e32 v56, v51, v56
	v_add_f32_e32 v57, v57, v60
	ds_bpermute_b32 v60, v162, v56
	ds_bpermute_b32 v61, v162, v57
	v_cvt_pk_bf16_f32 v51, v58, v59
	global_store_dwordx4 v[74:75], v[48:51], off
	v_cvt_pk_bf16_f32 v52, v52, v53
	v_cvt_pk_bf16_f32 v53, v54, v55
	s_waitcnt lgkmcnt(1)
	v_add_f32_e32 v48, v56, v60
	s_waitcnt lgkmcnt(0)
	v_add_f32_e32 v49, v57, v61
	ds_bpermute_b32 v50, v147, v48
	ds_bpermute_b32 v51, v147, v49
	v_cvt_pk_bf16_f32 v54, v68, v69
	v_cvt_pk_bf16_f32 v55, v66, v67
	global_store_dwordx4 v[74:75], v[52:55], off offset:256
	s_and_saveexec_b64 s[28:29], s[2:3]
	s_cbranch_execz .LBB0_706
	v_lshlrev_b32_e32 v52, 1, v64
	v_ashrrev_i32_e32 v53, 31, v52
	v_lshl_add_u64 v[52:53], v[52:53], 2, s[58:59]
	s_waitcnt lgkmcnt(1)
	v_add_f32_e32 v48, v48, v50
	s_waitcnt lgkmcnt(0)
	v_add_f32_e32 v49, v49, v51
	v_mov_b32_e32 v202, v48
	v_mov_b32_e32 v203, v49
.LBB0_706:
	s_or_b64 exec, exec, s[28:29]
	v_add_u32_e32 v48, 0x90, v146
	v_ashrrev_i32_e32 v49, 31, v48
	v_lshlrev_b64 v[58:59], 11, v[48:49]
	s_waitcnt lgkmcnt(0)
	v_lshl_add_u64 v[50:51], s[0:1], 0, v[58:59]
	v_lshl_add_u64 v[54:55], v[50:51], 0, v[144:145]
	global_load_dwordx4 v[50:53], v[54:55], off
	s_nop 0
	global_load_dwordx4 v[54:57], v[54:55], off offset:256
	v_lshl_add_u64 v[58:59], s[6:7], 0, v[58:59]
	v_lshl_add_u64 v[58:59], v[58:59], 0, v[144:145]
	s_waitcnt vmcnt(1)
	v_lshlrev_b32_e32 v60, 16, v50
	v_and_b32_e32 v61, 0xffff0000, v50
	v_lshlrev_b32_e32 v50, 16, v51
	v_and_b32_e32 v51, 0xffff0000, v51
	v_lshlrev_b32_e32 v62, 16, v52
	v_and_b32_e32 v63, 0xffff0000, v52
	v_lshlrev_b32_e32 v52, 16, v53
	v_and_b32_e32 v53, 0xffff0000, v53
	s_waitcnt vmcnt(0)
	v_lshlrev_b32_e32 v64, 16, v54
	v_and_b32_e32 v65, 0xffff0000, v54
	v_lshlrev_b32_e32 v54, 16, v55
	v_and_b32_e32 v55, 0xffff0000, v55
	v_lshlrev_b32_e32 v66, 16, v56
	v_and_b32_e32 v67, 0xffff0000, v56
	v_lshlrev_b32_e32 v56, 16, v57
	v_and_b32_e32 v57, 0xffff0000, v57
	v_pk_fma_f32 v[46:47], v[50:51], s[18:19], v[46:47] op_sel_hi:[1,0,1]
	v_pk_fma_f32 v[44:45], v[60:61], s[18:19], v[44:45] op_sel_hi:[1,0,1]
	v_pk_fma_f32 v[42:43], v[52:53], s[18:19], v[42:43] op_sel_hi:[1,0,1]
	v_pk_fma_f32 v[40:41], v[62:63], s[18:19], v[40:41] op_sel_hi:[1,0,1]
	v_pk_fma_f32 v[38:39], v[54:55], s[18:19], v[38:39] op_sel_hi:[1,0,1]
	v_pk_fma_f32 v[36:37], v[64:65], s[18:19], v[36:37] op_sel_hi:[1,0,1]
	v_pk_fma_f32 v[50:51], v[56:57], s[18:19], v[34:35] op_sel_hi:[1,0,1]
	v_pk_fma_f32 v[52:53], v[66:67], s[18:19], v[32:33] op_sel_hi:[1,0,1]
	v_cvt_pk_bf16_f32 v32, v44, v45
	v_cvt_pk_bf16_f32 v33, v46, v47
	v_cvt_pk_bf16_f32 v34, v40, v41
	v_add_f32_e32 v35, v44, v45
	v_add_f32_e32 v49, v46, v47
	v_add_f32_e32 v54, v40, v41
	v_add_f32_e32 v55, v42, v43
	v_mul_f32_e32 v45, v45, v45
	v_mul_f32_e32 v47, v47, v47
	v_mul_f32_e32 v41, v41, v41
	v_mul_f32_e32 v56, v43, v43
	v_add_f32_e32 v57, v36, v37
	v_add_f32_e32 v60, v38, v39
	v_add_f32_e32 v61, v52, v53
	v_add_f32_e32 v62, v50, v51
	v_mul_f32_e32 v63, v37, v37
	v_mul_f32_e32 v64, v39, v39
	v_mul_f32_e32 v65, v53, v53
	v_mul_f32_e32 v66, v51, v51
	v_add_f32_e32 v35, v35, v49
	v_add_f32_e32 v49, v54, v55
	v_fmac_f32_e32 v45, v44, v44
	v_fmac_f32_e32 v47, v46, v46
	v_fmac_f32_e32 v41, v40, v40
	v_fmac_f32_e32 v56, v42, v42
	v_add_f32_e32 v40, v57, v60
	v_add_f32_e32 v44, v61, v62
	v_fmac_f32_e32 v63, v36, v36
	v_fmac_f32_e32 v64, v38, v38
	v_fmac_f32_e32 v65, v52, v52
	v_fmac_f32_e32 v66, v50, v50
	v_add_f32_e32 v35, v35, v49
	v_add_f32_e32 v45, v45, v47
	v_add_f32_e32 v41, v41, v56
	v_add_f32_e32 v40, v40, v44
	v_add_f32_e32 v44, v63, v64
	v_add_f32_e32 v46, v65, v66
	v_add_f32_e32 v35, 0, v35
	v_add_f32_e32 v41, v45, v41
	v_add_f32_e32 v44, v44, v46
	v_add_f32_e32 v40, v35, v40
	v_add_f32_e32 v41, v41, v44
	ds_bpermute_b32 v44, v162, v40
	ds_bpermute_b32 v45, v162, v41
	v_cvt_pk_bf16_f32 v35, v42, v43
	global_store_dwordx4 v[58:59], v[32:35], off
	v_cvt_pk_bf16_f32 v36, v36, v37
	v_cvt_pk_bf16_f32 v37, v38, v39
	s_waitcnt lgkmcnt(1)
; __device__ __forceinline__ unsigned pk2(float lo, float hi) { f32x2v v = {lo, hi}; b16x2v b = __builtin_convertvector(v, b16x2v); return __builtin_bit_cast(unsigned, b); }
; __device__ __forceinline__ float bflo(unsigned v) { return __uint_as_float(v << 16); }
; __device__ __forceinline__ float bfhi(unsigned v) { return __uint_as_float(v & 0xffff0000u); }
;     __device__ __forceinline__ void operator()(const f32x4 (&acc)[2][2][4][2], const Unit& u, int wr, int wc, int fr, int fq) const {
;     ...
;                 const int row = u.pm * 256 + ai * 128 + wr * 64 + m * 16 + fr;
;                 float mu = 0.f, rs = 1.f;
;                 if (MODE == 1) { const f32x2v s2 = *(const f32x2v*)(stp + 2 * row); mu = s2.x * (1.0f / DM); rs = rsqrtf(fmaxf(s2.y * (1.0f / DM) - mu * mu, 0.f) + LN_EPS); }
;                 const bf16_t* xrow = xb + (size_t)row * DM + colb; bf16_t* orow = Rb + (size_t)row * DM + colb;
;                 float sum = 0.f, sq = 0.f;
; #pragma unroll
;                 for (int bj = 0; bj < 2; ++bj) {
;                     const u32x4 xw = *(const u32x4*)(xrow + 128 * bj);
;                     f32x4 x0 = {bflo(xw.x), bfhi(xw.x), bflo(xw.y), bfhi(xw.y)}, x1 = {bflo(xw.z), bfhi(xw.z), bflo(xw.w), bfhi(xw.w)};
;                     if (MODE == 1) { x0 = (x0 - mu) * rs * g4[bj][0] + b4[bj][0]; x1 = (x1 - mu) * rs * g4[bj][1] + b4[bj][1]; }
;                     const f32x4 r0 = x0 * DN_ALPHA + acc[ai][bj][m][0], r1 = x1 * DN_ALPHA + acc[ai][bj][m][1];
;                     u32x4 w; w.x = pk2(r0[0], r0[1]); w.y = pk2(r0[2], r0[3]); w.z = pk2(r1[0], r1[1]); w.w = pk2(r1[2], r1[3]);
;                     *(u32x4*)(orow + 128 * bj) = w;
;                     sum += ((r0[0] + r0[1]) + (r0[2] + r0[3])) + ((r1[0] + r1[1]) + (r1[2] + r1[3]));
;                     sq += ((r0[0] * r0[0] + r0[1] * r0[1]) + (r0[2] * r0[2] + r0[3] * r0[3])) + ((r1[0] * r1[0] + r1[1] * r1[1]) + (r1[2] * r1[2] + r1[3] * r1[3]));
;                 }
;                 sum += __shfl_xor(sum, 16); sum += __shfl_xor(sum, 32); sq += __shfl_xor(sq, 16); sq += __shfl_xor(sq, 32);
;                 if (fq == 0) { atomicAdd(st + 2 * row, sum); atomicAdd(st + 2 * row + 1, sq); }
	v_add_f32_e32 v32, v40, v44
	s_waitcnt lgkmcnt(0)
	v_add_f32_e32 v33, v41, v45
	ds_bpermute_b32 v34, v147, v32
	ds_bpermute_b32 v35, v147, v33
	v_cvt_pk_bf16_f32 v38, v52, v53
	v_cvt_pk_bf16_f32 v39, v50, v51
	global_store_dwordx4 v[58:59], v[36:39], off offset:256
	s_and_saveexec_b64 s[28:29], s[2:3]
	s_cbranch_execz .LBB0_708
	v_lshlrev_b32_e32 v36, 1, v48
	v_ashrrev_i32_e32 v37, 31, v36
	v_lshl_add_u64 v[36:37], v[36:37], 2, s[58:59]
	s_waitcnt lgkmcnt(1)
	v_add_f32_e32 v32, v32, v34
	s_waitcnt lgkmcnt(0)
	v_add_f32_e32 v33, v33, v35
	v_mov_b32_e32 v204, v32
	v_mov_b32_e32 v205, v33
.LBB0_708:
	s_or_b64 exec, exec, s[28:29]
	v_add_u32_e32 v32, 0xa0, v146
	v_ashrrev_i32_e32 v33, 31, v32
	v_lshlrev_b64 v[42:43], 11, v[32:33]
	s_waitcnt lgkmcnt(0)
	v_lshl_add_u64 v[34:35], s[0:1], 0, v[42:43]
	v_lshl_add_u64 v[38:39], v[34:35], 0, v[144:145]
	global_load_dwordx4 v[34:37], v[38:39], off
	s_nop 0
	global_load_dwordx4 v[38:41], v[38:39], off offset:256
	v_lshl_add_u64 v[42:43], s[6:7], 0, v[42:43]
	v_lshl_add_u64 v[42:43], v[42:43], 0, v[144:145]
	s_waitcnt vmcnt(1)
	v_lshlrev_b32_e32 v44, 16, v34
	v_and_b32_e32 v45, 0xffff0000, v34
	v_lshlrev_b32_e32 v34, 16, v35
	v_and_b32_e32 v35, 0xffff0000, v35
	v_lshlrev_b32_e32 v46, 16, v36
	v_and_b32_e32 v47, 0xffff0000, v36
	v_lshlrev_b32_e32 v36, 16, v37
	v_and_b32_e32 v37, 0xffff0000, v37
	s_waitcnt vmcnt(0)
	v_lshlrev_b32_e32 v48, 16, v38
	v_and_b32_e32 v49, 0xffff0000, v38
	v_lshlrev_b32_e32 v38, 16, v39
	v_and_b32_e32 v39, 0xffff0000, v39
	v_lshlrev_b32_e32 v50, 16, v40
	v_and_b32_e32 v51, 0xffff0000, v40
	v_lshlrev_b32_e32 v40, 16, v41
	v_and_b32_e32 v41, 0xffff0000, v41
	v_pk_fma_f32 v[30:31], v[34:35], s[18:19], v[30:31] op_sel_hi:[1,0,1]
	v_pk_fma_f32 v[28:29], v[44:45], s[18:19], v[28:29] op_sel_hi:[1,0,1]
	v_pk_fma_f32 v[26:27], v[36:37], s[18:19], v[26:27] op_sel_hi:[1,0,1]
	v_pk_fma_f32 v[24:25], v[46:47], s[18:19], v[24:25] op_sel_hi:[1,0,1]
	v_pk_fma_f32 v[22:23], v[38:39], s[18:19], v[22:23] op_sel_hi:[1,0,1]
	v_pk_fma_f32 v[20:21], v[48:49], s[18:19], v[20:21] op_sel_hi:[1,0,1]
	v_pk_fma_f32 v[34:35], v[40:41], s[18:19], v[18:19] op_sel_hi:[1,0,1]
	v_pk_fma_f32 v[36:37], v[50:51], s[18:19], v[16:17] op_sel_hi:[1,0,1]
	v_cvt_pk_bf16_f32 v16, v28, v29
	v_cvt_pk_bf16_f32 v17, v30, v31
	v_cvt_pk_bf16_f32 v18, v24, v25
	v_add_f32_e32 v19, v28, v29
	v_add_f32_e32 v33, v30, v31
	v_add_f32_e32 v38, v24, v25
	v_add_f32_e32 v39, v26, v27
	v_mul_f32_e32 v29, v29, v29
	v_mul_f32_e32 v31, v31, v31
	v_mul_f32_e32 v25, v25, v25
	v_mul_f32_e32 v40, v27, v27
	v_add_f32_e32 v41, v20, v21
	v_add_f32_e32 v44, v22, v23
	v_add_f32_e32 v45, v36, v37
	v_add_f32_e32 v46, v34, v35
	v_mul_f32_e32 v47, v21, v21
	v_mul_f32_e32 v48, v23, v23
	v_mul_f32_e32 v49, v37, v37
	v_mul_f32_e32 v50, v35, v35
	v_add_f32_e32 v19, v19, v33
	v_add_f32_e32 v33, v38, v39
	v_fmac_f32_e32 v29, v28, v28
	v_fmac_f32_e32 v31, v30, v30
	v_fmac_f32_e32 v25, v24, v24
	v_fmac_f32_e32 v40, v26, v26
	v_add_f32_e32 v24, v41, v44
	v_add_f32_e32 v28, v45, v46
	v_fmac_f32_e32 v47, v20, v20
	v_fmac_f32_e32 v48, v22, v22
	v_fmac_f32_e32 v49, v36, v36
	v_fmac_f32_e32 v50, v34, v34
	v_add_f32_e32 v19, v19, v33
	v_add_f32_e32 v29, v29, v31
	v_add_f32_e32 v25, v25, v40
	v_add_f32_e32 v24, v24, v28
	v_add_f32_e32 v28, v47, v48
	v_add_f32_e32 v30, v49, v50
	v_add_f32_e32 v19, 0, v19
	v_add_f32_e32 v25, v29, v25
	v_add_f32_e32 v28, v28, v30
	v_add_f32_e32 v24, v19, v24
	v_add_f32_e32 v25, v25, v28
	ds_bpermute_b32 v28, v162, v24
	ds_bpermute_b32 v29, v162, v25
	v_cvt_pk_bf16_f32 v19, v26, v27
	global_store_dwordx4 v[42:43], v[16:19], off
	v_cvt_pk_bf16_f32 v20, v20, v21
	v_cvt_pk_bf16_f32 v21, v22, v23
	s_waitcnt lgkmcnt(1)
	v_add_f32_e32 v16, v24, v28
	s_waitcnt lgkmcnt(0)
	v_add_f32_e32 v17, v25, v29
	ds_bpermute_b32 v18, v147, v16
	ds_bpermute_b32 v19, v147, v17
	v_cvt_pk_bf16_f32 v22, v36, v37
	v_cvt_pk_bf16_f32 v23, v34, v35
	global_store_dwordx4 v[42:43], v[20:23], off offset:256
	s_and_saveexec_b64 s[28:29], s[2:3]
	s_cbranch_execz .LBB0_710
	v_lshlrev_b32_e32 v20, 1, v32
	v_ashrrev_i32_e32 v21, 31, v20
	v_lshl_add_u64 v[20:21], v[20:21], 2, s[58:59]
	s_waitcnt lgkmcnt(1)
	v_add_f32_e32 v16, v16, v18
	s_waitcnt lgkmcnt(0)
	v_add_f32_e32 v17, v17, v19
	v_mov_b32_e32 v206, v16
	v_mov_b32_e32 v207, v17
; __device__ __forceinline__ unsigned pk2(float lo, float hi) { f32x2v v = {lo, hi}; b16x2v b = __builtin_convertvector(v, b16x2v); return __builtin_bit_cast(unsigned, b); }
; __device__ __forceinline__ float bflo(unsigned v) { return __uint_as_float(v << 16); }
; __device__ __forceinline__ float bfhi(unsigned v) { return __uint_as_float(v & 0xffff0000u); }
;     __device__ __forceinline__ void operator()(const f32x4 (&acc)[2][2][4][2], const Unit& u, int wr, int wc, int fr, int fq) const {
;     ...
;             for (int m = 0; m < 4; ++m) {
;                 const int row = u.pm * 256 + ai * 128 + wr * 64 + m * 16 + fr;
;                 float mu = 0.f, rs = 1.f;
;                 if (MODE == 1) { const f32x2v s2 = *(const f32x2v*)(stp + 2 * row); mu = s2.x * (1.0f / DM); rs = rsqrtf(fmaxf(s2.y * (1.0f / DM) - mu * mu, 0.f) + LN_EPS); }
;                 const bf16_t* xrow = xb + (size_t)row * DM + colb; bf16_t* orow = Rb + (size_t)row * DM + colb;
;                 float sum = 0.f, sq = 0.f;
; #pragma unroll
;                 for (int bj = 0; bj < 2; ++bj) {
;                     const u32x4 xw = *(const u32x4*)(xrow + 128 * bj);
;                     f32x4 x0 = {bflo(xw.x), bfhi(xw.x), bflo(xw.y), bfhi(xw.y)}, x1 = {bflo(xw.z), bfhi(xw.z), bflo(xw.w), bfhi(xw.w)};
;                     if (MODE == 1) { x0 = (x0 - mu) * rs * g4[bj][0] + b4[bj][0]; x1 = (x1 - mu) * rs * g4[bj][1] + b4[bj][1]; }
;                     const f32x4 r0 = x0 * DN_ALPHA + acc[ai][bj][m][0], r1 = x1 * DN_ALPHA + acc[ai][bj][m][1];
;                     u32x4 w; w.x = pk2(r0[0], r0[1]); w.y = pk2(r0[2], r0[3]); w.z = pk2(r1[0], r1[1]); w.w = pk2(r1[2], r1[3]);
;                     *(u32x4*)(orow + 128 * bj) = w;
;                     sum += ((r0[0] + r0[1]) + (r0[2] + r0[3])) + ((r1[0] + r1[1]) + (r1[2] + r1[3]));
;                     sq += ((r0[0] * r0[0] + r0[1] * r0[1]) + (r0[2] * r0[2] + r0[3] * r0[3])) + ((r1[0] * r1[0] + r1[1] * r1[1]) + (r1[2] * r1[2] + r1[3] * r1[3]));
;                 }
;                 sum += __shfl_xor(sum, 16); sum += __shfl_xor(sum, 32); sq += __shfl_xor(sq, 16); sq += __shfl_xor(sq, 32);
;                 if (fq == 0) { atomicAdd(st + 2 * row, sum); atomicAdd(st + 2 * row + 1, sq); }
.LBB0_710:
	s_or_b64 exec, exec, s[28:29]
	v_add_u32_e32 v16, 0xb0, v146
	v_ashrrev_i32_e32 v17, 31, v16
	v_lshlrev_b64 v[26:27], 11, v[16:17]
	s_waitcnt lgkmcnt(0)
	v_lshl_add_u64 v[18:19], s[0:1], 0, v[26:27]
	v_lshl_add_u64 v[22:23], v[18:19], 0, v[144:145]
	global_load_dwordx4 v[18:21], v[22:23], off
	s_nop 0
	global_load_dwordx4 v[22:25], v[22:23], off offset:256
	v_lshl_add_u64 v[26:27], s[6:7], 0, v[26:27]
	v_lshl_add_u64 v[26:27], v[26:27], 0, v[144:145]
	s_waitcnt vmcnt(1)
	v_lshlrev_b32_e32 v28, 16, v18
	v_and_b32_e32 v29, 0xffff0000, v18
	v_lshlrev_b32_e32 v18, 16, v19
	v_and_b32_e32 v19, 0xffff0000, v19
	v_lshlrev_b32_e32 v30, 16, v20
	v_and_b32_e32 v31, 0xffff0000, v20
	v_lshlrev_b32_e32 v20, 16, v21
	v_and_b32_e32 v21, 0xffff0000, v21
	s_waitcnt vmcnt(0)
	v_lshlrev_b32_e32 v32, 16, v22
	v_and_b32_e32 v33, 0xffff0000, v22
	v_lshlrev_b32_e32 v22, 16, v23
	v_and_b32_e32 v23, 0xffff0000, v23
	v_lshlrev_b32_e32 v34, 16, v24
	v_and_b32_e32 v35, 0xffff0000, v24
	v_lshlrev_b32_e32 v24, 16, v25
	v_and_b32_e32 v25, 0xffff0000, v25
	v_pk_fma_f32 v[14:15], v[18:19], s[18:19], v[14:15] op_sel_hi:[1,0,1]
	v_pk_fma_f32 v[12:13], v[28:29], s[18:19], v[12:13] op_sel_hi:[1,0,1]
	v_pk_fma_f32 v[10:11], v[20:21], s[18:19], v[10:11] op_sel_hi:[1,0,1]
	v_pk_fma_f32 v[8:9], v[30:31], s[18:19], v[8:9] op_sel_hi:[1,0,1]
	v_pk_fma_f32 v[6:7], v[22:23], s[18:19], v[6:7] op_sel_hi:[1,0,1]
	v_pk_fma_f32 v[4:5], v[32:33], s[18:19], v[4:5] op_sel_hi:[1,0,1]
	v_pk_fma_f32 v[18:19], v[24:25], s[18:19], v[2:3] op_sel_hi:[1,0,1]
	v_pk_fma_f32 v[20:21], v[34:35], s[18:19], v[0:1] op_sel_hi:[1,0,1]
	v_cvt_pk_bf16_f32 v0, v12, v13
	v_cvt_pk_bf16_f32 v1, v14, v15
	v_cvt_pk_bf16_f32 v2, v8, v9
	v_add_f32_e32 v3, v12, v13
	v_add_f32_e32 v17, v14, v15
	v_add_f32_e32 v22, v8, v9
	v_add_f32_e32 v23, v10, v11
	v_mul_f32_e32 v13, v13, v13
	v_mul_f32_e32 v15, v15, v15
	v_mul_f32_e32 v9, v9, v9
	v_mul_f32_e32 v24, v11, v11
	v_add_f32_e32 v25, v4, v5
	v_add_f32_e32 v28, v6, v7
	v_add_f32_e32 v29, v20, v21
	v_add_f32_e32 v30, v18, v19
	v_mul_f32_e32 v31, v5, v5
	v_mul_f32_e32 v32, v7, v7
	v_mul_f32_e32 v33, v21, v21
	v_mul_f32_e32 v34, v19, v19
	v_add_f32_e32 v3, v3, v17
	v_add_f32_e32 v17, v22, v23
	v_fmac_f32_e32 v13, v12, v12
	v_fmac_f32_e32 v15, v14, v14
	v_fmac_f32_e32 v9, v8, v8
	v_fmac_f32_e32 v24, v10, v10
	v_add_f32_e32 v8, v25, v28
	v_add_f32_e32 v12, v29, v30
	v_fmac_f32_e32 v31, v4, v4
	v_fmac_f32_e32 v32, v6, v6
	v_fmac_f32_e32 v33, v20, v20
	v_fmac_f32_e32 v34, v18, v18
	v_add_f32_e32 v3, v3, v17
	v_add_f32_e32 v13, v13, v15
	v_add_f32_e32 v9, v9, v24
	v_add_f32_e32 v8, v8, v12
	v_add_f32_e32 v12, v31, v32
	v_add_f32_e32 v14, v33, v34
	v_add_f32_e32 v3, 0, v3
	v_add_f32_e32 v9, v13, v9
	v_add_f32_e32 v12, v12, v14
	v_add_f32_e32 v8, v3, v8
	v_add_f32_e32 v9, v9, v12
	ds_bpermute_b32 v12, v162, v8
	ds_bpermute_b32 v13, v162, v9
	v_cvt_pk_bf16_f32 v3, v10, v11
	global_store_dwordx4 v[26:27], v[0:3], off
	v_cvt_pk_bf16_f32 v4, v4, v5
	v_cvt_pk_bf16_f32 v5, v6, v7
	s_waitcnt lgkmcnt(1)
	v_add_f32_e32 v0, v8, v12
	s_waitcnt lgkmcnt(0)
	v_add_f32_e32 v1, v9, v13
	ds_bpermute_b32 v2, v147, v0
	ds_bpermute_b32 v3, v147, v1
	v_cvt_pk_bf16_f32 v6, v20, v21
	v_cvt_pk_bf16_f32 v7, v18, v19
	global_store_dwordx4 v[26:27], v[4:7], off offset:256
	s_and_saveexec_b64 s[28:29], s[2:3]
	s_cbranch_execz .LBB0_712
	v_lshlrev_b32_e32 v4, 1, v16
	v_ashrrev_i32_e32 v5, 31, v4
	v_lshl_add_u64 v[4:5], v[4:5], 2, s[58:59]
	s_waitcnt lgkmcnt(1)
	v_add_f32_e32 v0, v0, v2
	s_waitcnt lgkmcnt(0)
	v_add_f32_e32 v1, v1, v3
	v_mov_b32_e32 v208, v0
	v_mov_b32_e32 v209, v1
.LBB0_712:
	s_or_b64 exec, exec, s[28:29]
	s_and_saveexec_b64 s[98:99], s[2:3]
	s_cbranch_execz .Ldefat_p3
	v_lshlrev_b32_e32 v210, 1, v146
	v_ashrrev_i32_e32 v211, 31, v210
	v_lshl_add_u64 v[210:211], v[210:211], 2, s[58:59]
	global_atomic_add_f32 v[210:211], v194, off
	global_atomic_add_f32 v[210:211], v195, off offset:4
	global_atomic_add_f32 v[210:211], v196, off offset:128
	global_atomic_add_f32 v[210:211], v197, off offset:132
	global_atomic_add_f32 v[210:211], v198, off offset:256
	global_atomic_add_f32 v[210:211], v199, off offset:260
	global_atomic_add_f32 v[210:211], v200, off offset:384
	global_atomic_add_f32 v[210:211], v201, off offset:388
	global_atomic_add_f32 v[210:211], v202, off offset:1024
	global_atomic_add_f32 v[210:211], v203, off offset:1028
	global_atomic_add_f32 v[210:211], v204, off offset:1152
	global_atomic_add_f32 v[210:211], v205, off offset:1156
	global_atomic_add_f32 v[210:211], v206, off offset:1280
	global_atomic_add_f32 v[210:211], v207, off offset:1284
	global_atomic_add_f32 v[210:211], v208, off offset:1408
	global_atomic_add_f32 v[210:211], v209, off offset:1412
.Ldefat_p3:
	s_or_b64 exec, exec, s[98:99]
	s_andn2_b64 vcc, exec, s[4:5]
	s_mov_b64 s[4:5], -1
	s_cbranch_vccnz .LBB0_685
	s_andn2_b64 vcc, exec, s[12:13]
	s_cbranch_vccnz .LBB0_684
	s_barrier
	s_branch .LBB0_684

; __device__ __forceinline__ unsigned pk2(float lo, float hi) { f32x2v v = {lo, hi}; b16x2v b = __builtin_convertvector(v, b16x2v); return __builtin_bit_cast(unsigned, b); }
; __device__ __forceinline__ float bflo(unsigned v) { return __uint_as_float(v << 16); }
;     __device__ __forceinline__ void operator()(const f32x4 (&acc)[2][2][4][2], const Unit& u, int wr, int wc, int fr, int fq) const {
;     ...
;         if (MODE == 1) {
; #pragma unroll
;             for (int bj = 0; bj < 2; ++bj)
; #pragma unroll
;                 for (int n = 0; n < 2; ++n) { const int col = colb + 128 * bj + 4 * n; g4[bj][n] = *(const f32x4*)(g + col); b4[bj][n] = *(const f32x4*)(b + col); }
;         }
; #pragma unroll
;         for (int ai = 0; ai < 2; ++ai)
; #pragma unroll
;             for (int m = 0; m < 4; ++m) {
;                 const int row = u.pm * 256 + ai * 128 + wr * 64 + m * 16 + fr;
;                 float mu = 0.f, rs = 1.f;
;                 if (MODE == 1) { const f32x2v s2 = *(const f32x2v*)(stp + 2 * row); mu = s2.x * (1.0f / DM); rs = rsqrtf(fmaxf(s2.y * (1.0f / DM) - mu * mu, 0.f) + LN_EPS); }
;                 const bf16_t* xrow = xb + (size_t)row * DM + colb; bf16_t* orow = Rb + (size_t)row * DM + colb;
;                 float sum = 0.f, sq = 0.f;
; #pragma unroll
;                 for (int bj = 0; bj < 2; ++bj) {
;                     const u32x4 xw = *(const u32x4*)(xrow + 128 * bj);
;                     f32x4 x0 = {bflo(xw.x), bfhi(xw.x), bflo(xw.y), bfhi(xw.y)}, x1 = {bflo(xw.z), bfhi(xw.z), bflo(xw.w), bfhi(xw.w)};
;                     if (MODE == 1) { x0 = (x0 - mu) * rs * g4[bj][0] + b4[bj][0]; x1 = (x1 - mu) * rs * g4[bj][1] + b4[bj][1]; }
;                     const f32x4 r0 = x0 * DN_ALPHA + acc[ai][bj][m][0], r1 = x1 * DN_ALPHA + acc[ai][bj][m][1];
;                     u32x4 w; w.x = pk2(r0[0], r0[1]); w.y = pk2(r0[2], r0[3]); w.z = pk2(r1[0], r1[1]); w.w = pk2(r1[2], r1[3]);
;                     *(u32x4*)(orow + 128 * bj) = w;
;                     sum += ((r0[0] + r0[1]) + (r0[2] + r0[3])) + ((r1[0] + r1[1]) + (r1[2] + r1[3]));
;                     sq += ((r0[0] * r0[0] + r0[1] * r0[1]) + (r0[2] * r0[2] + r0[3] * r0[3])) + ((r1[0] * r1[0] + r1[1] * r1[1]) + (r1[2] * r1[2] + r1[3] * r1[3]));
;                 }
;                 sum += __shfl_xor(sum, 16); sum += __shfl_xor(sum, 32); sq += __shfl_xor(sq, 16); sq += __shfl_xor(sq, 32);
.LBB0_1015:
	v_lshl_add_u32 v178, s34, 8, v189
	v_lshlrev_b32_e32 v180, 1, v178
	v_ashrrev_i32_e32 v181, 31, v180
	v_lshl_add_u64 v[66:67], v[180:181], 2, s[58:59]
	v_lshl_or_b32 v64, s36, 8, v191
	global_load_dwordx2 v[208:209], v[66:67], off
	v_ashrrev_i32_e32 v179, 31, v178
	v_ashrrev_i32_e32 v65, 31, v64
	v_lshlrev_b64 v[210:211], 11, v[178:179]
	v_lshl_add_u64 v[66:67], s[0:1], 0, v[210:211]
	v_lshlrev_b64 v[176:177], 1, v[64:65]
	v_lshl_add_u64 v[66:67], v[66:67], 0, v[176:177]
	global_load_dwordx4 v[200:203], v[66:67], off
	global_load_dwordx4 v[204:207], v[66:67], off offset:256
	v_readlane_b32 s68, v242, 3
	v_lshlrev_b64 v[64:65], 2, v[64:65]
	v_readlane_b32 s70, v242, 5
	v_readlane_b32 s71, v242, 6
	v_readlane_b32 s69, v242, 4
	v_and_b32_e32 v81, 64, v197
	v_lshl_add_u64 v[92:93], s[70:71], 0, v[64:65]
	v_lshl_add_u64 v[84:85], s[68:69], 0, v[64:65]
	global_load_dwordx4 v[64:67], v[92:93], off
	global_load_dwordx4 v[76:79], v[84:85], off
	global_load_dwordx4 v[68:71], v[84:85], off offset:16
	global_load_dwordx4 v[72:75], v[92:93], off offset:16
	v_xor_b32_e32 v80, 16, v197
	v_add_u32_e32 v81, 64, v81
	v_xor_b32_e32 v82, 32, v197
	v_cmp_lt_i32_e32 vcc, v80, v81
	v_lshl_add_u64 v[210:211], s[6:7], 0, v[210:211]
	v_lshl_add_u64 v[210:211], v[210:211], 0, v[176:177]
	v_cndmask_b32_e32 v179, v197, v80, vcc
	v_cmp_lt_i32_e32 vcc, v82, v81
	v_lshlrev_b32_e32 v198, 2, v179
	v_readlane_b32 s72, v242, 7
	v_cndmask_b32_e32 v199, v197, v82, vcc
	global_load_dwordx4 v[80:83], v[84:85], off offset:528
	global_load_dwordx4 v[88:91], v[84:85], off offset:512
	s_nop 0
	global_load_dwordx4 v[84:87], v[92:93], off offset:528
	s_nop 0
	global_load_dwordx4 v[92:95], v[92:93], off offset:512
	v_lshlrev_b32_e32 v179, 2, v199
	v_readlane_b32 s73, v242, 8
	v_readlane_b32 s74, v242, 9
	v_readlane_b32 s75, v242, 10
	v_readlane_b32 s76, v242, 11
	v_readlane_b32 s77, v242, 12
	v_readlane_b32 s78, v242, 13
	v_readlane_b32 s79, v242, 14
	v_readlane_b32 s80, v242, 15
	v_readlane_b32 s81, v242, 16
	v_readlane_b32 s82, v242, 17
	v_readlane_b32 s83, v242, 18
	s_waitcnt vmcnt(0)
	v_pk_mul_f32 v[208:209], v[208:209], s[20:21] op_sel_hi:[1,0]
	s_nop 0
	v_fma_f32 v199, -v208, v208, v209
	v_max_f32_e32 v199, 0, v199
	v_add_f32_e32 v199, 0x3727c5ac, v199
	v_cmp_gt_f32_e32 vcc, s65, v199
	v_lshlrev_b32_e32 v209, 16, v200
	v_lshlrev_b32_e32 v218, 16, v204
	v_and_b32_e32 v219, 0xffff0000, v204
	v_mul_f32_e32 v204, 0x4b800000, v199
	v_cndmask_b32_e32 v199, v199, v204, vcc
	v_rsq_f32_e32 v199, v199
	v_and_b32_e32 v200, 0xffff0000, v200
	v_lshlrev_b32_e32 v212, 16, v201
	v_and_b32_e32 v213, 0xffff0000, v201
	v_lshlrev_b32_e32 v214, 16, v202
	v_and_b32_e32 v215, 0xffff0000, v202
	v_lshlrev_b32_e32 v216, 16, v203
	v_and_b32_e32 v217, 0xffff0000, v203
	v_sub_f32_e32 v201, v200, v208
	v_sub_f32_e32 v200, v209, v208
	v_mul_f32_e32 v209, 0x45800000, v199
	v_lshlrev_b32_e32 v220, 16, v205
	v_and_b32_e32 v221, 0xffff0000, v205
	v_sub_f32_e32 v203, v213, v208
	v_sub_f32_e32 v202, v212, v208
	v_sub_f32_e32 v205, v215, v208
	v_sub_f32_e32 v204, v214, v208
	v_sub_f32_e32 v213, v217, v208
	v_sub_f32_e32 v212, v216, v208
	v_cndmask_b32_e32 v214, v199, v209, vcc
	v_pk_mul_f32 v[202:203], v[202:203], v[214:215] op_sel_hi:[1,0]
	v_pk_mul_f32 v[200:201], v[200:201], v[214:215] op_sel_hi:[1,0]
	v_pk_mul_f32 v[212:213], v[212:213], v[214:215] op_sel_hi:[1,0]
	v_pk_mul_f32 v[204:205], v[204:205], v[214:215] op_sel_hi:[1,0]
	v_pk_fma_f32 v[200:201], v[76:77], v[200:201], v[64:65]
	v_pk_fma_f32 v[202:203], v[78:79], v[202:203], v[66:67]
	v_pk_fma_f32 v[204:205], v[68:69], v[204:205], v[72:73]
	v_pk_fma_f32 v[212:213], v[70:71], v[212:213], v[74:75]
	v_pk_fma_f32 v[158:159], v[202:203], s[22:23], v[158:159] op_sel_hi:[1,0,1]
	v_pk_fma_f32 v[156:157], v[200:201], s[22:23], v[156:157] op_sel_hi:[1,0,1]
	v_pk_fma_f32 v[200:201], v[212:213], s[22:23], v[154:155] op_sel_hi:[1,0,1]
	v_pk_fma_f32 v[202:203], v[204:205], s[22:23], v[152:153] op_sel_hi:[1,0,1]
	v_cvt_pk_bf16_f32 v152, v156, v157
	v_cvt_pk_bf16_f32 v153, v158, v159
	v_cvt_pk_bf16_f32 v154, v202, v203
	v_cvt_pk_bf16_f32 v155, v200, v201
	v_add_f32_e32 v199, v156, v157
	v_add_f32_e32 v204, v158, v159
	v_add_f32_e32 v205, v202, v203
	v_add_f32_e32 v209, v200, v201
	v_mul_f32_e32 v157, v157, v157
	v_mul_f32_e32 v159, v159, v159
	v_mul_f32_e32 v203, v203, v203
	v_mul_f32_e32 v201, v201, v201
	v_add_f32_e32 v199, v199, v204
	v_add_f32_e32 v204, v205, v209
	v_fmac_f32_e32 v157, v156, v156
	v_fmac_f32_e32 v159, v158, v158
	v_fmac_f32_e32 v203, v202, v202
	v_fmac_f32_e32 v201, v200, v200
	v_add_f32_e32 v156, v199, v204
	v_add_f32_e32 v157, v157, v159
	v_add_f32_e32 v158, v203, v201
	v_lshlrev_b32_e32 v222, 16, v206
	v_add_f32_e32 v199, 0, v156
	v_add_f32_e32 v204, v157, v158
	v_and_b32_e32 v200, 0xffff0000, v206
	v_lshlrev_b32_e32 v202, 16, v207
	v_and_b32_e32 v203, 0xffff0000, v207
	v_sub_f32_e32 v157, v219, v208
	v_sub_f32_e32 v156, v218, v208
	v_sub_f32_e32 v159, v221, v208
	v_sub_f32_e32 v158, v220, v208
	v_pk_mul_f32 v[158:159], v[158:159], v[214:215] op_sel_hi:[1,0]
	v_pk_mul_f32 v[156:157], v[156:157], v[214:215] op_sel_hi:[1,0]
	v_sub_f32_e32 v201, v200, v208
	v_sub_f32_e32 v200, v222, v208
	v_sub_f32_e32 v203, v203, v208
	v_sub_f32_e32 v202, v202, v208
	v_pk_fma_f32 v[156:157], v[88:89], v[156:157], v[92:93]
	v_pk_fma_f32 v[158:159], v[90:91], v[158:159], v[94:95]
	v_pk_mul_f32 v[202:203], v[202:203], v[214:215] op_sel_hi:[1,0]
	v_pk_mul_f32 v[200:201], v[200:201], v[214:215] op_sel_hi:[1,0]
	v_pk_fma_f32 v[202:203], v[82:83], v[202:203], v[86:87]
	v_pk_fma_f32 v[200:201], v[80:81], v[200:201], v[84:85]
	v_pk_fma_f32 v[150:151], v[158:159], s[22:23], v[150:151] op_sel_hi:[1,0,1]
	v_pk_fma_f32 v[148:149], v[156:157], s[22:23], v[148:149] op_sel_hi:[1,0,1]
	v_pk_fma_f32 v[156:157], v[202:203], s[22:23], v[146:147] op_sel_hi:[1,0,1]
	v_pk_fma_f32 v[158:159], v[200:201], s[22:23], v[144:145] op_sel_hi:[1,0,1]
	v_add_f32_e32 v144, v148, v149
	v_add_f32_e32 v145, v150, v151
	v_add_f32_e32 v144, v144, v145
	v_add_f32_e32 v145, v158, v159
	v_add_f32_e32 v146, v156, v157
	v_add_f32_e32 v145, v145, v146
	v_add_f32_e32 v144, v144, v145
	v_mul_f32_e32 v145, v149, v149
	v_mul_f32_e32 v146, v151, v151
	v_fmac_f32_e32 v145, v148, v148
	v_fmac_f32_e32 v146, v150, v150
	v_add_f32_e32 v145, v145, v146
	v_mul_f32_e32 v146, v159, v159
	v_mul_f32_e32 v147, v157, v157
	v_fmac_f32_e32 v146, v158, v158
	v_fmac_f32_e32 v147, v156, v156
	v_add_f32_e32 v146, v146, v147
	v_add_f32_e32 v145, v145, v146
	v_add_f32_e32 v144, v144, v199
	v_add_f32_e32 v147, v204, v145
	ds_bpermute_b32 v146, v198, v144
	ds_bpermute_b32 v199, v198, v147
	v_cvt_pk_bf16_f32 v148, v148, v149
	v_cvt_pk_bf16_f32 v149, v150, v151
	v_cvt_pk_bf16_f32 v150, v158, v159
	s_waitcnt lgkmcnt(1)
; __device__ __forceinline__ unsigned pk2(float lo, float hi) { f32x2v v = {lo, hi}; b16x2v b = __builtin_convertvector(v, b16x2v); return __builtin_bit_cast(unsigned, b); }
; __device__ __forceinline__ float bflo(unsigned v) { return __uint_as_float(v << 16); }
; __device__ __forceinline__ float bfhi(unsigned v) { return __uint_as_float(v & 0xffff0000u); }
;     __device__ __forceinline__ void operator()(const f32x4 (&acc)[2][2][4][2], const Unit& u, int wr, int wc, int fr, int fq) const {
;     ...
;             for (int m = 0; m < 4; ++m) {
;                 const int row = u.pm * 256 + ai * 128 + wr * 64 + m * 16 + fr;
;                 float mu = 0.f, rs = 1.f;
;                 if (MODE == 1) { const f32x2v s2 = *(const f32x2v*)(stp + 2 * row); mu = s2.x * (1.0f / DM); rs = rsqrtf(fmaxf(s2.y * (1.0f / DM) - mu * mu, 0.f) + LN_EPS); }
;                 const bf16_t* xrow = xb + (size_t)row * DM + colb; bf16_t* orow = Rb + (size_t)row * DM + colb;
;                 float sum = 0.f, sq = 0.f;
; #pragma unroll
;                 for (int bj = 0; bj < 2; ++bj) {
;                     const u32x4 xw = *(const u32x4*)(xrow + 128 * bj);
;                     f32x4 x0 = {bflo(xw.x), bfhi(xw.x), bflo(xw.y), bfhi(xw.y)}, x1 = {bflo(xw.z), bfhi(xw.z), bflo(xw.w), bfhi(xw.w)};
;                     if (MODE == 1) { x0 = (x0 - mu) * rs * g4[bj][0] + b4[bj][0]; x1 = (x1 - mu) * rs * g4[bj][1] + b4[bj][1]; }
;                     const f32x4 r0 = x0 * DN_ALPHA + acc[ai][bj][m][0], r1 = x1 * DN_ALPHA + acc[ai][bj][m][1];
;                     u32x4 w; w.x = pk2(r0[0], r0[1]); w.y = pk2(r0[2], r0[3]); w.z = pk2(r1[0], r1[1]); w.w = pk2(r1[2], r1[3]);
;                     *(u32x4*)(orow + 128 * bj) = w;
;                     sum += ((r0[0] + r0[1]) + (r0[2] + r0[3])) + ((r1[0] + r1[1]) + (r1[2] + r1[3]));
;                     sq += ((r0[0] * r0[0] + r0[1] * r0[1]) + (r0[2] * r0[2] + r0[3] * r0[3])) + ((r1[0] * r1[0] + r1[1] * r1[1]) + (r1[2] * r1[2] + r1[3] * r1[3]));
;                 }
;                 sum += __shfl_xor(sum, 16); sum += __shfl_xor(sum, 32); sq += __shfl_xor(sq, 16); sq += __shfl_xor(sq, 32);
;                 if (fq == 0) { atomicAdd(st + 2 * row, sum); atomicAdd(st + 2 * row + 1, sq); }
	v_add_f32_e32 v144, v144, v146
	s_waitcnt lgkmcnt(0)
	v_add_f32_e32 v146, v147, v199
	ds_bpermute_b32 v145, v179, v144
	ds_bpermute_b32 v147, v179, v146
	v_cvt_pk_bf16_f32 v151, v156, v157
	global_store_dwordx4 v[210:211], v[152:155], off
	global_store_dwordx4 v[210:211], v[148:151], off offset:256
	s_and_saveexec_b64 s[34:35], s[2:3]
	s_cbranch_execz .LBB0_1017
	v_lshl_add_u64 v[148:149], v[180:181], 2, s[8:9]
	s_waitcnt lgkmcnt(1)
	v_add_f32_e32 v144, v144, v145
	s_waitcnt lgkmcnt(0)
	v_add_f32_e32 v145, v146, v147
	v_mov_b32_e32 v223, v144
	v_mov_b32_e32 v224, v145
.LBB0_1017:
	s_or_b64 exec, exec, s[34:35]
	v_or_b32_e32 v146, 16, v178
	v_lshlrev_b32_e32 v144, 1, v146
	s_waitcnt lgkmcnt(1)
	v_ashrrev_i32_e32 v145, 31, v144
	v_lshl_add_u64 v[148:149], v[144:145], 2, s[58:59]
	global_load_dwordx2 v[154:155], v[148:149], off
	s_waitcnt lgkmcnt(0)
	v_ashrrev_i32_e32 v147, 31, v146
	v_lshlrev_b64 v[156:157], 11, v[146:147]
	v_lshl_add_u64 v[146:147], s[0:1], 0, v[156:157]
	v_lshl_add_u64 v[150:151], v[146:147], 0, v[176:177]
	global_load_dwordx4 v[146:149], v[150:151], off
	s_nop 0
	global_load_dwordx4 v[150:153], v[150:151], off offset:256
	v_lshl_add_u64 v[156:157], s[6:7], 0, v[156:157]
	v_lshl_add_u64 v[156:157], v[156:157], 0, v[176:177]
	s_waitcnt vmcnt(2)
	v_pk_mul_f32 v[154:155], v[154:155], s[20:21] op_sel_hi:[1,0]
	s_nop 0
	v_fma_f32 v155, -v154, v154, v155
	v_max_f32_e32 v155, 0, v155
	v_add_f32_e32 v155, 0x3727c5ac, v155
	s_waitcnt vmcnt(1)
	v_and_b32_e32 v199, 0xffff0000, v148
	s_waitcnt vmcnt(0)
	v_lshlrev_b32_e32 v204, 16, v151
	v_and_b32_e32 v205, 0xffff0000, v151
	v_sub_f32_e32 v151, v199, v154
	v_mul_f32_e32 v199, 0x4b800000, v155
	v_cmp_gt_f32_e32 vcc, s65, v155
	v_lshlrev_b32_e32 v158, 16, v146
	v_and_b32_e32 v146, 0xffff0000, v146
	v_cndmask_b32_e32 v155, v155, v199, vcc
	v_rsq_f32_e32 v199, v155
	v_lshlrev_b32_e32 v202, 16, v150
	v_lshlrev_b32_e32 v159, 16, v147
	v_and_b32_e32 v180, 0xffff0000, v147
	v_lshlrev_b32_e32 v181, 16, v148
	v_lshlrev_b32_e32 v200, 16, v149
	v_and_b32_e32 v201, 0xffff0000, v149
	v_sub_f32_e32 v147, v146, v154
	v_sub_f32_e32 v146, v158, v154
	v_sub_f32_e32 v158, v202, v154
	v_mul_f32_e32 v202, 0x45800000, v199
	v_and_b32_e32 v203, 0xffff0000, v150
	v_lshlrev_b32_e32 v206, 16, v152
	v_and_b32_e32 v207, 0xffff0000, v152
	v_lshlrev_b32_e32 v208, 16, v153
	v_and_b32_e32 v209, 0xffff0000, v153
	v_sub_f32_e32 v149, v180, v154
	v_sub_f32_e32 v148, v159, v154
	v_sub_f32_e32 v150, v181, v154
	v_sub_f32_e32 v153, v201, v154
	v_sub_f32_e32 v152, v200, v154
	v_cndmask_b32_e32 v202, v199, v202, vcc
	v_sub_f32_e32 v159, v203, v154
	v_sub_f32_e32 v181, v205, v154
	v_sub_f32_e32 v180, v204, v154
	v_sub_f32_e32 v201, v207, v154
	v_sub_f32_e32 v200, v206, v154
	v_sub_f32_e32 v155, v209, v154
	v_sub_f32_e32 v154, v208, v154
	v_pk_mul_f32 v[148:149], v[148:149], v[202:203] op_sel_hi:[1,0]
	v_pk_mul_f32 v[146:147], v[146:147], v[202:203] op_sel_hi:[1,0]
	v_pk_mul_f32 v[152:153], v[152:153], v[202:203] op_sel_hi:[1,0]
	v_pk_mul_f32 v[150:151], v[150:151], v[202:203] op_sel_hi:[1,0]
	v_pk_mul_f32 v[154:155], v[154:155], v[202:203] op_sel_hi:[1,0]
	v_pk_mul_f32 v[200:201], v[200:201], v[202:203] op_sel_hi:[1,0]
	v_pk_fma_f32 v[146:147], v[76:77], v[146:147], v[64:65]
	v_pk_fma_f32 v[148:149], v[78:79], v[148:149], v[66:67]
	v_pk_fma_f32 v[150:151], v[68:69], v[150:151], v[72:73]
	v_pk_fma_f32 v[152:153], v[70:71], v[152:153], v[74:75]
	v_pk_fma_f32 v[200:201], v[80:81], v[200:201], v[84:85]
	v_pk_fma_f32 v[154:155], v[82:83], v[154:155], v[86:87]
	v_pk_fma_f32 v[142:143], v[148:149], s[22:23], v[142:143] op_sel_hi:[1,0,1]
	v_pk_fma_f32 v[140:141], v[146:147], s[22:23], v[140:141] op_sel_hi:[1,0,1]
	v_pk_fma_f32 v[138:139], v[152:153], s[22:23], v[138:139] op_sel_hi:[1,0,1]
	v_pk_fma_f32 v[136:137], v[150:151], s[22:23], v[136:137] op_sel_hi:[1,0,1]
	v_pk_mul_f32 v[180:181], v[180:181], v[202:203] op_sel_hi:[1,0]
	v_pk_mul_f32 v[158:159], v[158:159], v[202:203] op_sel_hi:[1,0]
	v_pk_fma_f32 v[146:147], v[154:155], s[22:23], v[130:131] op_sel_hi:[1,0,1]
	v_pk_fma_f32 v[148:149], v[200:201], s[22:23], v[128:129] op_sel_hi:[1,0,1]
	v_cvt_pk_bf16_f32 v128, v140, v141
	v_cvt_pk_bf16_f32 v129, v142, v143
	v_cvt_pk_bf16_f32 v130, v136, v137
	v_cvt_pk_bf16_f32 v131, v138, v139
	v_add_f32_e32 v150, v140, v141
	v_add_f32_e32 v151, v142, v143
	v_add_f32_e32 v152, v136, v137
	v_add_f32_e32 v153, v138, v139
	v_mul_f32_e32 v141, v141, v141
	v_mul_f32_e32 v143, v143, v143
	v_mul_f32_e32 v137, v137, v137
	v_mul_f32_e32 v139, v139, v139
	v_pk_fma_f32 v[158:159], v[88:89], v[158:159], v[92:93]
	v_pk_fma_f32 v[180:181], v[90:91], v[180:181], v[94:95]
	v_fmac_f32_e32 v141, v140, v140
	v_fmac_f32_e32 v143, v142, v142
	v_fmac_f32_e32 v137, v136, v136
	v_fmac_f32_e32 v139, v138, v138
	v_pk_fma_f32 v[134:135], v[180:181], s[22:23], v[134:135] op_sel_hi:[1,0,1]
	v_pk_fma_f32 v[132:133], v[158:159], s[22:23], v[132:133] op_sel_hi:[1,0,1]
	v_add_f32_e32 v138, v141, v143
	v_add_f32_e32 v137, v137, v139
	v_add_f32_e32 v154, v132, v133
	v_add_f32_e32 v150, v150, v151
	v_add_f32_e32 v151, v152, v153
	v_add_f32_e32 v137, v138, v137
	v_add_f32_e32 v138, v134, v135
	v_add_f32_e32 v139, v148, v149
	v_add_f32_e32 v140, v146, v147
	v_add_f32_e32 v136, v150, v151
	v_add_f32_e32 v138, v154, v138
	v_add_f32_e32 v139, v139, v140
	v_add_f32_e32 v136, 0, v136
	v_add_f32_e32 v138, v138, v139
	v_add_f32_e32 v136, v138, v136
	v_mul_f32_e32 v138, v133, v133
	v_mul_f32_e32 v139, v135, v135
	v_fmac_f32_e32 v138, v132, v132
	v_fmac_f32_e32 v139, v134, v134
	v_add_f32_e32 v138, v138, v139
	v_mul_f32_e32 v139, v149, v149
	v_mul_f32_e32 v140, v147, v147
	v_fmac_f32_e32 v139, v148, v148
	v_fmac_f32_e32 v140, v146, v146
	v_add_f32_e32 v139, v139, v140
	v_add_f32_e32 v138, v138, v139
	v_add_f32_e32 v137, v137, v138
	ds_bpermute_b32 v139, v198, v136
	ds_bpermute_b32 v138, v198, v137
	global_store_dwordx4 v[156:157], v[128:131], off
	v_cvt_pk_bf16_f32 v132, v132, v133
	v_cvt_pk_bf16_f32 v133, v134, v135
	s_waitcnt lgkmcnt(1)
	v_add_f32_e32 v128, v136, v139
	s_waitcnt lgkmcnt(0)
	v_add_f32_e32 v130, v137, v138
	ds_bpermute_b32 v129, v179, v128
	ds_bpermute_b32 v131, v179, v130
	v_cvt_pk_bf16_f32 v134, v148, v149
	v_cvt_pk_bf16_f32 v135, v146, v147
	global_store_dwordx4 v[156:157], v[132:135], off offset:256
	s_and_saveexec_b64 s[34:35], s[2:3]
	s_cbranch_execz .LBB0_1019
	v_lshl_add_u64 v[132:133], v[144:145], 2, s[8:9]
	s_waitcnt lgkmcnt(1)
	v_add_f32_e32 v128, v128, v129
	s_waitcnt lgkmcnt(0)
	v_add_f32_e32 v129, v130, v131
	v_mov_b32_e32 v225, v128
	v_mov_b32_e32 v226, v129
; __device__ __forceinline__ unsigned pk2(float lo, float hi) { f32x2v v = {lo, hi}; b16x2v b = __builtin_convertvector(v, b16x2v); return __builtin_bit_cast(unsigned, b); }
; __device__ __forceinline__ float bflo(unsigned v) { return __uint_as_float(v << 16); }
; __device__ __forceinline__ float bfhi(unsigned v) { return __uint_as_float(v & 0xffff0000u); }
;     __device__ __forceinline__ void operator()(const f32x4 (&acc)[2][2][4][2], const Unit& u, int wr, int wc, int fr, int fq) const {
;     ...
;             for (int m = 0; m < 4; ++m) {
;                 const int row = u.pm * 256 + ai * 128 + wr * 64 + m * 16 + fr;
;                 float mu = 0.f, rs = 1.f;
;                 if (MODE == 1) { const f32x2v s2 = *(const f32x2v*)(stp + 2 * row); mu = s2.x * (1.0f / DM); rs = rsqrtf(fmaxf(s2.y * (1.0f / DM) - mu * mu, 0.f) + LN_EPS); }
;                 const bf16_t* xrow = xb + (size_t)row * DM + colb; bf16_t* orow = Rb + (size_t)row * DM + colb;
;                 float sum = 0.f, sq = 0.f;
; #pragma unroll
;                 for (int bj = 0; bj < 2; ++bj) {
;                     const u32x4 xw = *(const u32x4*)(xrow + 128 * bj);
;                     f32x4 x0 = {bflo(xw.x), bfhi(xw.x), bflo(xw.y), bfhi(xw.y)}, x1 = {bflo(xw.z), bfhi(xw.z), bflo(xw.w), bfhi(xw.w)};
;                     if (MODE == 1) { x0 = (x0 - mu) * rs * g4[bj][0] + b4[bj][0]; x1 = (x1 - mu) * rs * g4[bj][1] + b4[bj][1]; }
;                     const f32x4 r0 = x0 * DN_ALPHA + acc[ai][bj][m][0], r1 = x1 * DN_ALPHA + acc[ai][bj][m][1];
;                     u32x4 w; w.x = pk2(r0[0], r0[1]); w.y = pk2(r0[2], r0[3]); w.z = pk2(r1[0], r1[1]); w.w = pk2(r1[2], r1[3]);
;                     *(u32x4*)(orow + 128 * bj) = w;
;                     sum += ((r0[0] + r0[1]) + (r0[2] + r0[3])) + ((r1[0] + r1[1]) + (r1[2] + r1[3]));
;                     sq += ((r0[0] * r0[0] + r0[1] * r0[1]) + (r0[2] * r0[2] + r0[3] * r0[3])) + ((r1[0] * r1[0] + r1[1] * r1[1]) + (r1[2] * r1[2] + r1[3] * r1[3]));
;                 }
;                 sum += __shfl_xor(sum, 16); sum += __shfl_xor(sum, 32); sq += __shfl_xor(sq, 16); sq += __shfl_xor(sq, 32);
;                 if (fq == 0) { atomicAdd(st + 2 * row, sum); atomicAdd(st + 2 * row + 1, sq); }
.LBB0_1019:
	s_or_b64 exec, exec, s[34:35]
	v_or_b32_e32 v130, 32, v178
	v_lshlrev_b32_e32 v128, 1, v130
	s_waitcnt lgkmcnt(1)
	v_ashrrev_i32_e32 v129, 31, v128
	v_lshl_add_u64 v[132:133], v[128:129], 2, s[58:59]
	global_load_dwordx2 v[138:139], v[132:133], off
	s_waitcnt lgkmcnt(0)
	v_ashrrev_i32_e32 v131, 31, v130
	v_lshlrev_b64 v[140:141], 11, v[130:131]
	v_lshl_add_u64 v[130:131], s[0:1], 0, v[140:141]
	v_lshl_add_u64 v[134:135], v[130:131], 0, v[176:177]
	global_load_dwordx4 v[130:133], v[134:135], off
	s_nop 0
	global_load_dwordx4 v[134:137], v[134:135], off offset:256
	v_lshl_add_u64 v[140:141], s[6:7], 0, v[140:141]
	v_lshl_add_u64 v[140:141], v[140:141], 0, v[176:177]
	s_waitcnt vmcnt(2)
	v_pk_mul_f32 v[138:139], v[138:139], s[20:21] op_sel_hi:[1,0]
	s_nop 0
	v_fma_f32 v139, -v138, v138, v139
	v_max_f32_e32 v139, 0, v139
	v_add_f32_e32 v139, 0x3727c5ac, v139
	s_waitcnt vmcnt(1)
	v_and_b32_e32 v146, 0xffff0000, v132
	s_waitcnt vmcnt(0)
	v_lshlrev_b32_e32 v151, 16, v135
	v_and_b32_e32 v152, 0xffff0000, v135
	v_sub_f32_e32 v135, v146, v138
	v_mul_f32_e32 v146, 0x4b800000, v139
	v_cmp_gt_f32_e32 vcc, s65, v139
	v_and_b32_e32 v148, 0xffff0000, v133
	v_lshlrev_b32_e32 v155, 16, v137
	v_cndmask_b32_e32 v139, v139, v146, vcc
	v_and_b32_e32 v156, 0xffff0000, v137
	v_sub_f32_e32 v137, v148, v138
	v_rsq_f32_e32 v148, v139
	v_lshlrev_b32_e32 v142, 16, v130
	v_and_b32_e32 v130, 0xffff0000, v130
	v_lshlrev_b32_e32 v149, 16, v134
	v_lshlrev_b32_e32 v143, 16, v131
	v_and_b32_e32 v144, 0xffff0000, v131
	v_lshlrev_b32_e32 v145, 16, v132
	v_lshlrev_b32_e32 v147, 16, v133
	v_sub_f32_e32 v131, v130, v138
	v_sub_f32_e32 v130, v142, v138
	v_sub_f32_e32 v142, v149, v138
	v_mul_f32_e32 v149, 0x45800000, v148
	v_and_b32_e32 v150, 0xffff0000, v134
	v_lshlrev_b32_e32 v153, 16, v136
	v_and_b32_e32 v154, 0xffff0000, v136
	v_sub_f32_e32 v133, v144, v138
	v_sub_f32_e32 v132, v143, v138
	v_sub_f32_e32 v134, v145, v138
	v_sub_f32_e32 v136, v147, v138
	v_cndmask_b32_e32 v148, v148, v149, vcc
	v_sub_f32_e32 v143, v150, v138
	v_sub_f32_e32 v145, v152, v138
	v_sub_f32_e32 v144, v151, v138
	v_sub_f32_e32 v147, v154, v138
	v_sub_f32_e32 v146, v153, v138
	v_sub_f32_e32 v139, v156, v138
	v_sub_f32_e32 v138, v155, v138
	v_pk_mul_f32 v[132:133], v[132:133], v[148:149] op_sel_hi:[1,0]
	v_pk_mul_f32 v[130:131], v[130:131], v[148:149] op_sel_hi:[1,0]
	v_pk_mul_f32 v[136:137], v[136:137], v[148:149] op_sel_hi:[1,0]
	v_pk_mul_f32 v[134:135], v[134:135], v[148:149] op_sel_hi:[1,0]
	v_pk_mul_f32 v[138:139], v[138:139], v[148:149] op_sel_hi:[1,0]
	v_pk_mul_f32 v[146:147], v[146:147], v[148:149] op_sel_hi:[1,0]
	v_pk_fma_f32 v[130:131], v[76:77], v[130:131], v[64:65]
	v_pk_fma_f32 v[132:133], v[78:79], v[132:133], v[66:67]
	v_pk_fma_f32 v[134:135], v[68:69], v[134:135], v[72:73]
	v_pk_fma_f32 v[136:137], v[70:71], v[136:137], v[74:75]
	v_pk_fma_f32 v[146:147], v[80:81], v[146:147], v[84:85]
	v_pk_fma_f32 v[138:139], v[82:83], v[138:139], v[86:87]
	v_pk_fma_f32 v[126:127], v[132:133], s[22:23], v[126:127] op_sel_hi:[1,0,1]
	v_pk_fma_f32 v[124:125], v[130:131], s[22:23], v[124:125] op_sel_hi:[1,0,1]
	v_pk_fma_f32 v[122:123], v[136:137], s[22:23], v[122:123] op_sel_hi:[1,0,1]
	v_pk_fma_f32 v[120:121], v[134:135], s[22:23], v[120:121] op_sel_hi:[1,0,1]
	v_pk_mul_f32 v[144:145], v[144:145], v[148:149] op_sel_hi:[1,0]
	v_pk_mul_f32 v[142:143], v[142:143], v[148:149] op_sel_hi:[1,0]
	v_pk_fma_f32 v[130:131], v[138:139], s[22:23], v[114:115] op_sel_hi:[1,0,1]
	v_pk_fma_f32 v[132:133], v[146:147], s[22:23], v[112:113] op_sel_hi:[1,0,1]
	v_cvt_pk_bf16_f32 v112, v124, v125
	v_cvt_pk_bf16_f32 v113, v126, v127
	v_cvt_pk_bf16_f32 v114, v120, v121
	v_cvt_pk_bf16_f32 v115, v122, v123
	v_add_f32_e32 v134, v124, v125
	v_add_f32_e32 v135, v126, v127
	v_add_f32_e32 v136, v120, v121
	v_add_f32_e32 v137, v122, v123
	v_mul_f32_e32 v125, v125, v125
	v_mul_f32_e32 v127, v127, v127
	v_mul_f32_e32 v121, v121, v121
	v_mul_f32_e32 v123, v123, v123
	v_pk_fma_f32 v[142:143], v[88:89], v[142:143], v[92:93]
	v_pk_fma_f32 v[144:145], v[90:91], v[144:145], v[94:95]
	v_fmac_f32_e32 v125, v124, v124
	v_fmac_f32_e32 v127, v126, v126
	v_fmac_f32_e32 v121, v120, v120
	v_fmac_f32_e32 v123, v122, v122
	v_pk_fma_f32 v[118:119], v[144:145], s[22:23], v[118:119] op_sel_hi:[1,0,1]
	v_pk_fma_f32 v[116:117], v[142:143], s[22:23], v[116:117] op_sel_hi:[1,0,1]
	v_add_f32_e32 v122, v125, v127
	v_add_f32_e32 v121, v121, v123
	v_add_f32_e32 v138, v116, v117
	v_add_f32_e32 v134, v134, v135
	v_add_f32_e32 v135, v136, v137
	v_add_f32_e32 v121, v122, v121
	v_add_f32_e32 v122, v118, v119
	v_add_f32_e32 v123, v132, v133
	v_add_f32_e32 v124, v130, v131
	v_add_f32_e32 v120, v134, v135
	v_add_f32_e32 v122, v138, v122
	v_add_f32_e32 v123, v123, v124
	v_add_f32_e32 v120, 0, v120
	v_add_f32_e32 v122, v122, v123
	v_add_f32_e32 v120, v122, v120
	v_mul_f32_e32 v122, v117, v117
	v_mul_f32_e32 v123, v119, v119
	v_fmac_f32_e32 v122, v116, v116
	v_fmac_f32_e32 v123, v118, v118
	v_add_f32_e32 v122, v122, v123
	v_mul_f32_e32 v123, v133, v133
	v_mul_f32_e32 v124, v131, v131
	v_fmac_f32_e32 v123, v132, v132
	v_fmac_f32_e32 v124, v130, v130
	v_add_f32_e32 v123, v123, v124
	v_add_f32_e32 v122, v122, v123
	v_add_f32_e32 v121, v121, v122
	ds_bpermute_b32 v123, v198, v120
	ds_bpermute_b32 v122, v198, v121
	global_store_dwordx4 v[140:141], v[112:115], off
	v_cvt_pk_bf16_f32 v116, v116, v117
	v_cvt_pk_bf16_f32 v117, v118, v119
	s_waitcnt lgkmcnt(1)
	v_add_f32_e32 v112, v120, v123
	s_waitcnt lgkmcnt(0)
	v_add_f32_e32 v114, v121, v122
	ds_bpermute_b32 v113, v179, v112
	ds_bpermute_b32 v115, v179, v114
	v_cvt_pk_bf16_f32 v118, v132, v133
	v_cvt_pk_bf16_f32 v119, v130, v131
	global_store_dwordx4 v[140:141], v[116:119], off offset:256
	s_and_saveexec_b64 s[34:35], s[2:3]
	s_cbranch_execz .LBB0_1021
	v_lshl_add_u64 v[116:117], v[128:129], 2, s[8:9]
	s_waitcnt lgkmcnt(1)
	v_add_f32_e32 v112, v112, v113
	s_waitcnt lgkmcnt(0)
	v_add_f32_e32 v113, v114, v115
	v_mov_b32_e32 v227, v112
	v_mov_b32_e32 v228, v113
; __device__ __forceinline__ unsigned pk2(float lo, float hi) { f32x2v v = {lo, hi}; b16x2v b = __builtin_convertvector(v, b16x2v); return __builtin_bit_cast(unsigned, b); }
; __device__ __forceinline__ float bflo(unsigned v) { return __uint_as_float(v << 16); }
; __device__ __forceinline__ float bfhi(unsigned v) { return __uint_as_float(v & 0xffff0000u); }
;     __device__ __forceinline__ void operator()(const f32x4 (&acc)[2][2][4][2], const Unit& u, int wr, int wc, int fr, int fq) const {
;     ...
;             for (int m = 0; m < 4; ++m) {
;                 const int row = u.pm * 256 + ai * 128 + wr * 64 + m * 16 + fr;
;                 float mu = 0.f, rs = 1.f;
;                 if (MODE == 1) { const f32x2v s2 = *(const f32x2v*)(stp + 2 * row); mu = s2.x * (1.0f / DM); rs = rsqrtf(fmaxf(s2.y * (1.0f / DM) - mu * mu, 0.f) + LN_EPS); }
;                 const bf16_t* xrow = xb + (size_t)row * DM + colb; bf16_t* orow = Rb + (size_t)row * DM + colb;
;                 float sum = 0.f, sq = 0.f;
; #pragma unroll
;                 for (int bj = 0; bj < 2; ++bj) {
;                     const u32x4 xw = *(const u32x4*)(xrow + 128 * bj);
;                     f32x4 x0 = {bflo(xw.x), bfhi(xw.x), bflo(xw.y), bfhi(xw.y)}, x1 = {bflo(xw.z), bfhi(xw.z), bflo(xw.w), bfhi(xw.w)};
;                     if (MODE == 1) { x0 = (x0 - mu) * rs * g4[bj][0] + b4[bj][0]; x1 = (x1 - mu) * rs * g4[bj][1] + b4[bj][1]; }
;                     const f32x4 r0 = x0 * DN_ALPHA + acc[ai][bj][m][0], r1 = x1 * DN_ALPHA + acc[ai][bj][m][1];
;                     u32x4 w; w.x = pk2(r0[0], r0[1]); w.y = pk2(r0[2], r0[3]); w.z = pk2(r1[0], r1[1]); w.w = pk2(r1[2], r1[3]);
;                     *(u32x4*)(orow + 128 * bj) = w;
;                     sum += ((r0[0] + r0[1]) + (r0[2] + r0[3])) + ((r1[0] + r1[1]) + (r1[2] + r1[3]));
;                     sq += ((r0[0] * r0[0] + r0[1] * r0[1]) + (r0[2] * r0[2] + r0[3] * r0[3])) + ((r1[0] * r1[0] + r1[1] * r1[1]) + (r1[2] * r1[2] + r1[3] * r1[3]));
;                 }
;                 sum += __shfl_xor(sum, 16); sum += __shfl_xor(sum, 32); sq += __shfl_xor(sq, 16); sq += __shfl_xor(sq, 32);
;                 if (fq == 0) { atomicAdd(st + 2 * row, sum); atomicAdd(st + 2 * row + 1, sq); }
.LBB0_1021:
	s_or_b64 exec, exec, s[34:35]
	v_or_b32_e32 v114, 48, v178
	v_lshlrev_b32_e32 v112, 1, v114
	s_waitcnt lgkmcnt(1)
	v_ashrrev_i32_e32 v113, 31, v112
	v_lshl_add_u64 v[116:117], v[112:113], 2, s[58:59]
	global_load_dwordx2 v[122:123], v[116:117], off
	s_waitcnt lgkmcnt(0)
	v_ashrrev_i32_e32 v115, 31, v114
	v_lshlrev_b64 v[124:125], 11, v[114:115]
	v_lshl_add_u64 v[114:115], s[0:1], 0, v[124:125]
	v_lshl_add_u64 v[118:119], v[114:115], 0, v[176:177]
	global_load_dwordx4 v[114:117], v[118:119], off
	s_nop 0
	global_load_dwordx4 v[118:121], v[118:119], off offset:256
	v_lshl_add_u64 v[124:125], s[6:7], 0, v[124:125]
	v_lshl_add_u64 v[124:125], v[124:125], 0, v[176:177]
	s_waitcnt vmcnt(2)
	v_pk_mul_f32 v[122:123], v[122:123], s[20:21] op_sel_hi:[1,0]
	s_nop 0
	v_fma_f32 v123, -v122, v122, v123
	v_max_f32_e32 v123, 0, v123
	v_add_f32_e32 v123, 0x3727c5ac, v123
	s_waitcnt vmcnt(1)
	v_and_b32_e32 v130, 0xffff0000, v116
	s_waitcnt vmcnt(0)
	v_lshlrev_b32_e32 v135, 16, v119
	v_and_b32_e32 v136, 0xffff0000, v119
	v_sub_f32_e32 v119, v130, v122
	v_mul_f32_e32 v130, 0x4b800000, v123
	v_cmp_gt_f32_e32 vcc, s65, v123
	v_and_b32_e32 v132, 0xffff0000, v117
	v_lshlrev_b32_e32 v139, 16, v121
	v_cndmask_b32_e32 v123, v123, v130, vcc
	v_and_b32_e32 v140, 0xffff0000, v121
	v_sub_f32_e32 v121, v132, v122
	v_rsq_f32_e32 v132, v123
	v_lshlrev_b32_e32 v126, 16, v114
	v_and_b32_e32 v114, 0xffff0000, v114
	v_lshlrev_b32_e32 v133, 16, v118
	v_lshlrev_b32_e32 v127, 16, v115
	v_and_b32_e32 v128, 0xffff0000, v115
	v_lshlrev_b32_e32 v129, 16, v116
	v_lshlrev_b32_e32 v131, 16, v117
	v_sub_f32_e32 v115, v114, v122
	v_sub_f32_e32 v114, v126, v122
	v_sub_f32_e32 v126, v133, v122
	v_mul_f32_e32 v133, 0x45800000, v132
	v_and_b32_e32 v134, 0xffff0000, v118
	v_lshlrev_b32_e32 v137, 16, v120
	v_and_b32_e32 v138, 0xffff0000, v120
	v_sub_f32_e32 v117, v128, v122
	v_sub_f32_e32 v116, v127, v122
	v_sub_f32_e32 v118, v129, v122
	v_sub_f32_e32 v120, v131, v122
	v_cndmask_b32_e32 v132, v132, v133, vcc
	v_sub_f32_e32 v127, v134, v122
	v_sub_f32_e32 v129, v136, v122
	v_sub_f32_e32 v128, v135, v122
	v_sub_f32_e32 v131, v138, v122
	v_sub_f32_e32 v130, v137, v122
	v_sub_f32_e32 v123, v140, v122
	v_sub_f32_e32 v122, v139, v122
	v_pk_mul_f32 v[116:117], v[116:117], v[132:133] op_sel_hi:[1,0]
	v_pk_mul_f32 v[114:115], v[114:115], v[132:133] op_sel_hi:[1,0]
	v_pk_mul_f32 v[120:121], v[120:121], v[132:133] op_sel_hi:[1,0]
	v_pk_mul_f32 v[118:119], v[118:119], v[132:133] op_sel_hi:[1,0]
	v_pk_mul_f32 v[122:123], v[122:123], v[132:133] op_sel_hi:[1,0]
	v_pk_mul_f32 v[130:131], v[130:131], v[132:133] op_sel_hi:[1,0]
	v_pk_fma_f32 v[114:115], v[76:77], v[114:115], v[64:65]
	v_pk_fma_f32 v[116:117], v[78:79], v[116:117], v[66:67]
	v_pk_fma_f32 v[118:119], v[68:69], v[118:119], v[72:73]
	v_pk_fma_f32 v[120:121], v[70:71], v[120:121], v[74:75]
	v_pk_fma_f32 v[130:131], v[80:81], v[130:131], v[84:85]
	v_pk_fma_f32 v[122:123], v[82:83], v[122:123], v[86:87]
	v_pk_fma_f32 v[110:111], v[116:117], s[22:23], v[110:111] op_sel_hi:[1,0,1]
	v_pk_fma_f32 v[108:109], v[114:115], s[22:23], v[108:109] op_sel_hi:[1,0,1]
	v_pk_fma_f32 v[106:107], v[120:121], s[22:23], v[106:107] op_sel_hi:[1,0,1]
	v_pk_fma_f32 v[104:105], v[118:119], s[22:23], v[104:105] op_sel_hi:[1,0,1]
	v_pk_mul_f32 v[128:129], v[128:129], v[132:133] op_sel_hi:[1,0]
	v_pk_mul_f32 v[126:127], v[126:127], v[132:133] op_sel_hi:[1,0]
	v_pk_fma_f32 v[114:115], v[122:123], s[22:23], v[98:99] op_sel_hi:[1,0,1]
	v_pk_fma_f32 v[116:117], v[130:131], s[22:23], v[96:97] op_sel_hi:[1,0,1]
	v_cvt_pk_bf16_f32 v96, v108, v109
	v_cvt_pk_bf16_f32 v97, v110, v111
	v_cvt_pk_bf16_f32 v98, v104, v105
	v_cvt_pk_bf16_f32 v99, v106, v107
	v_add_f32_e32 v118, v108, v109
	v_add_f32_e32 v119, v110, v111
	v_add_f32_e32 v120, v104, v105
	v_add_f32_e32 v121, v106, v107
	v_mul_f32_e32 v109, v109, v109
	v_mul_f32_e32 v111, v111, v111
	v_mul_f32_e32 v105, v105, v105
	v_mul_f32_e32 v107, v107, v107
	v_pk_fma_f32 v[126:127], v[88:89], v[126:127], v[92:93]
	v_pk_fma_f32 v[128:129], v[90:91], v[128:129], v[94:95]
	v_fmac_f32_e32 v109, v108, v108
	v_fmac_f32_e32 v111, v110, v110
	v_fmac_f32_e32 v105, v104, v104
	v_fmac_f32_e32 v107, v106, v106
	v_pk_fma_f32 v[102:103], v[128:129], s[22:23], v[102:103] op_sel_hi:[1,0,1]
	v_pk_fma_f32 v[100:101], v[126:127], s[22:23], v[100:101] op_sel_hi:[1,0,1]
	v_add_f32_e32 v106, v109, v111
	v_add_f32_e32 v105, v105, v107
	v_add_f32_e32 v122, v100, v101
	v_add_f32_e32 v118, v118, v119
	v_add_f32_e32 v119, v120, v121
	v_add_f32_e32 v105, v106, v105
	v_add_f32_e32 v106, v102, v103
	v_add_f32_e32 v107, v116, v117
	v_add_f32_e32 v108, v114, v115
	v_add_f32_e32 v104, v118, v119
	v_add_f32_e32 v106, v122, v106
	v_add_f32_e32 v107, v107, v108
	v_add_f32_e32 v104, 0, v104
	v_add_f32_e32 v106, v106, v107
	v_add_f32_e32 v104, v106, v104
	v_mul_f32_e32 v106, v101, v101
	v_mul_f32_e32 v107, v103, v103
	v_fmac_f32_e32 v106, v100, v100
	v_fmac_f32_e32 v107, v102, v102
	v_add_f32_e32 v106, v106, v107
	v_mul_f32_e32 v107, v117, v117
	v_mul_f32_e32 v108, v115, v115
	v_fmac_f32_e32 v107, v116, v116
	v_fmac_f32_e32 v108, v114, v114
	v_add_f32_e32 v107, v107, v108
	v_add_f32_e32 v106, v106, v107
	v_add_f32_e32 v105, v105, v106
	ds_bpermute_b32 v107, v198, v104
	ds_bpermute_b32 v106, v198, v105
	global_store_dwordx4 v[124:125], v[96:99], off
	v_cvt_pk_bf16_f32 v100, v100, v101
	v_cvt_pk_bf16_f32 v101, v102, v103
	s_waitcnt lgkmcnt(1)
	v_add_f32_e32 v96, v104, v107
	s_waitcnt lgkmcnt(0)
	v_add_f32_e32 v98, v105, v106
	ds_bpermute_b32 v97, v179, v96
	ds_bpermute_b32 v99, v179, v98
	v_cvt_pk_bf16_f32 v102, v116, v117
	v_cvt_pk_bf16_f32 v103, v114, v115
	global_store_dwordx4 v[124:125], v[100:103], off offset:256
	s_and_saveexec_b64 s[34:35], s[2:3]
	s_cbranch_execz .LBB0_1023
	v_lshl_add_u64 v[100:101], v[112:113], 2, s[8:9]
	s_waitcnt lgkmcnt(1)
	v_add_f32_e32 v96, v96, v97
	s_waitcnt lgkmcnt(0)
	v_add_f32_e32 v97, v98, v99
	v_mov_b32_e32 v229, v96
	v_mov_b32_e32 v230, v97
; __device__ __forceinline__ unsigned pk2(float lo, float hi) { f32x2v v = {lo, hi}; b16x2v b = __builtin_convertvector(v, b16x2v); return __builtin_bit_cast(unsigned, b); }
; __device__ __forceinline__ float bflo(unsigned v) { return __uint_as_float(v << 16); }
; __device__ __forceinline__ float bfhi(unsigned v) { return __uint_as_float(v & 0xffff0000u); }
;     __device__ __forceinline__ void operator()(const f32x4 (&acc)[2][2][4][2], const Unit& u, int wr, int wc, int fr, int fq) const {
;     ...
;             for (int m = 0; m < 4; ++m) {
;                 const int row = u.pm * 256 + ai * 128 + wr * 64 + m * 16 + fr;
;                 float mu = 0.f, rs = 1.f;
;                 if (MODE == 1) { const f32x2v s2 = *(const f32x2v*)(stp + 2 * row); mu = s2.x * (1.0f / DM); rs = rsqrtf(fmaxf(s2.y * (1.0f / DM) - mu * mu, 0.f) + LN_EPS); }
;                 const bf16_t* xrow = xb + (size_t)row * DM + colb; bf16_t* orow = Rb + (size_t)row * DM + colb;
;                 float sum = 0.f, sq = 0.f;
; #pragma unroll
;                 for (int bj = 0; bj < 2; ++bj) {
;                     const u32x4 xw = *(const u32x4*)(xrow + 128 * bj);
;                     f32x4 x0 = {bflo(xw.x), bfhi(xw.x), bflo(xw.y), bfhi(xw.y)}, x1 = {bflo(xw.z), bfhi(xw.z), bflo(xw.w), bfhi(xw.w)};
;                     if (MODE == 1) { x0 = (x0 - mu) * rs * g4[bj][0] + b4[bj][0]; x1 = (x1 - mu) * rs * g4[bj][1] + b4[bj][1]; }
;                     const f32x4 r0 = x0 * DN_ALPHA + acc[ai][bj][m][0], r1 = x1 * DN_ALPHA + acc[ai][bj][m][1];
;                     u32x4 w; w.x = pk2(r0[0], r0[1]); w.y = pk2(r0[2], r0[3]); w.z = pk2(r1[0], r1[1]); w.w = pk2(r1[2], r1[3]);
;                     *(u32x4*)(orow + 128 * bj) = w;
;                     sum += ((r0[0] + r0[1]) + (r0[2] + r0[3])) + ((r1[0] + r1[1]) + (r1[2] + r1[3]));
;                     sq += ((r0[0] * r0[0] + r0[1] * r0[1]) + (r0[2] * r0[2] + r0[3] * r0[3])) + ((r1[0] * r1[0] + r1[1] * r1[1]) + (r1[2] * r1[2] + r1[3] * r1[3]));
;                 }
;                 sum += __shfl_xor(sum, 16); sum += __shfl_xor(sum, 32); sq += __shfl_xor(sq, 16); sq += __shfl_xor(sq, 32);
;                 if (fq == 0) { atomicAdd(st + 2 * row, sum); atomicAdd(st + 2 * row + 1, sq); }
.LBB0_1023:
	s_or_b64 exec, exec, s[34:35]
	v_add_u32_e32 v98, 0x80, v178
	v_lshlrev_b32_e32 v96, 1, v98
	s_waitcnt lgkmcnt(1)
	v_ashrrev_i32_e32 v97, 31, v96
	v_lshl_add_u64 v[100:101], v[96:97], 2, s[58:59]
	global_load_dwordx2 v[106:107], v[100:101], off
	s_waitcnt lgkmcnt(0)
	v_ashrrev_i32_e32 v99, 31, v98
	v_lshlrev_b64 v[108:109], 11, v[98:99]
	v_lshl_add_u64 v[98:99], s[0:1], 0, v[108:109]
	v_lshl_add_u64 v[102:103], v[98:99], 0, v[176:177]
	global_load_dwordx4 v[98:101], v[102:103], off
	s_nop 0
	global_load_dwordx4 v[102:105], v[102:103], off offset:256
	v_lshl_add_u64 v[108:109], s[6:7], 0, v[108:109]
	v_lshl_add_u64 v[108:109], v[108:109], 0, v[176:177]
	s_waitcnt vmcnt(2)
	v_pk_mul_f32 v[106:107], v[106:107], s[20:21] op_sel_hi:[1,0]
	s_nop 0
	v_fma_f32 v107, -v106, v106, v107
	v_max_f32_e32 v107, 0, v107
	v_add_f32_e32 v107, 0x3727c5ac, v107
	s_waitcnt vmcnt(1)
	v_and_b32_e32 v114, 0xffff0000, v100
	s_waitcnt vmcnt(0)
	v_lshlrev_b32_e32 v119, 16, v103
	v_and_b32_e32 v120, 0xffff0000, v103
	v_sub_f32_e32 v103, v114, v106
	v_mul_f32_e32 v114, 0x4b800000, v107
	v_cmp_gt_f32_e32 vcc, s65, v107
	v_and_b32_e32 v116, 0xffff0000, v101
	v_lshlrev_b32_e32 v123, 16, v105
	v_cndmask_b32_e32 v107, v107, v114, vcc
	v_and_b32_e32 v124, 0xffff0000, v105
	v_sub_f32_e32 v105, v116, v106
	v_rsq_f32_e32 v116, v107
	v_lshlrev_b32_e32 v110, 16, v98
	v_and_b32_e32 v98, 0xffff0000, v98
	v_lshlrev_b32_e32 v117, 16, v102
	v_lshlrev_b32_e32 v111, 16, v99
	v_and_b32_e32 v112, 0xffff0000, v99
	v_lshlrev_b32_e32 v113, 16, v100
	v_lshlrev_b32_e32 v115, 16, v101
	v_sub_f32_e32 v99, v98, v106
	v_sub_f32_e32 v98, v110, v106
	v_sub_f32_e32 v110, v117, v106
	v_mul_f32_e32 v117, 0x45800000, v116
	v_and_b32_e32 v118, 0xffff0000, v102
	v_lshlrev_b32_e32 v121, 16, v104
	v_and_b32_e32 v122, 0xffff0000, v104
	v_sub_f32_e32 v101, v112, v106
	v_sub_f32_e32 v100, v111, v106
	v_sub_f32_e32 v102, v113, v106
	v_sub_f32_e32 v104, v115, v106
	v_cndmask_b32_e32 v116, v116, v117, vcc
	v_sub_f32_e32 v111, v118, v106
	v_sub_f32_e32 v113, v120, v106
	v_sub_f32_e32 v112, v119, v106
	v_sub_f32_e32 v115, v122, v106
	v_sub_f32_e32 v114, v121, v106
	v_sub_f32_e32 v107, v124, v106
	v_sub_f32_e32 v106, v123, v106
	v_pk_mul_f32 v[100:101], v[100:101], v[116:117] op_sel_hi:[1,0]
	v_pk_mul_f32 v[98:99], v[98:99], v[116:117] op_sel_hi:[1,0]
	v_pk_mul_f32 v[104:105], v[104:105], v[116:117] op_sel_hi:[1,0]
	v_pk_mul_f32 v[102:103], v[102:103], v[116:117] op_sel_hi:[1,0]
	v_pk_mul_f32 v[106:107], v[106:107], v[116:117] op_sel_hi:[1,0]
	v_pk_mul_f32 v[114:115], v[114:115], v[116:117] op_sel_hi:[1,0]
	v_pk_fma_f32 v[98:99], v[76:77], v[98:99], v[64:65]
	v_pk_fma_f32 v[100:101], v[78:79], v[100:101], v[66:67]
	v_pk_fma_f32 v[102:103], v[68:69], v[102:103], v[72:73]
	v_pk_fma_f32 v[104:105], v[70:71], v[104:105], v[74:75]
	v_pk_fma_f32 v[114:115], v[80:81], v[114:115], v[84:85]
	v_pk_fma_f32 v[106:107], v[82:83], v[106:107], v[86:87]
	v_pk_fma_f32 v[62:63], v[100:101], s[22:23], v[62:63] op_sel_hi:[1,0,1]
	v_pk_fma_f32 v[60:61], v[98:99], s[22:23], v[60:61] op_sel_hi:[1,0,1]
	v_pk_fma_f32 v[58:59], v[104:105], s[22:23], v[58:59] op_sel_hi:[1,0,1]
	v_pk_fma_f32 v[56:57], v[102:103], s[22:23], v[56:57] op_sel_hi:[1,0,1]
	v_pk_mul_f32 v[112:113], v[112:113], v[116:117] op_sel_hi:[1,0]
	v_pk_mul_f32 v[110:111], v[110:111], v[116:117] op_sel_hi:[1,0]
	v_pk_fma_f32 v[98:99], v[106:107], s[22:23], v[50:51] op_sel_hi:[1,0,1]
	v_pk_fma_f32 v[100:101], v[114:115], s[22:23], v[48:49] op_sel_hi:[1,0,1]
	v_cvt_pk_bf16_f32 v48, v60, v61
	v_cvt_pk_bf16_f32 v49, v62, v63
	v_cvt_pk_bf16_f32 v50, v56, v57
	v_cvt_pk_bf16_f32 v51, v58, v59
	v_add_f32_e32 v102, v60, v61
	v_add_f32_e32 v103, v62, v63
	v_add_f32_e32 v104, v56, v57
	v_add_f32_e32 v105, v58, v59
	v_mul_f32_e32 v61, v61, v61
	v_mul_f32_e32 v63, v63, v63
	v_mul_f32_e32 v57, v57, v57
	v_mul_f32_e32 v59, v59, v59
	v_pk_fma_f32 v[110:111], v[88:89], v[110:111], v[92:93]
	v_pk_fma_f32 v[112:113], v[90:91], v[112:113], v[94:95]
	v_fmac_f32_e32 v61, v60, v60
	v_fmac_f32_e32 v63, v62, v62
	v_fmac_f32_e32 v57, v56, v56
	v_fmac_f32_e32 v59, v58, v58
	v_pk_fma_f32 v[54:55], v[112:113], s[22:23], v[54:55] op_sel_hi:[1,0,1]
	v_pk_fma_f32 v[52:53], v[110:111], s[22:23], v[52:53] op_sel_hi:[1,0,1]
	v_add_f32_e32 v58, v61, v63
	v_add_f32_e32 v57, v57, v59
	v_add_f32_e32 v106, v52, v53
	v_add_f32_e32 v102, v102, v103
	v_add_f32_e32 v103, v104, v105
	v_add_f32_e32 v57, v58, v57
	v_add_f32_e32 v58, v54, v55
	v_add_f32_e32 v59, v100, v101
	v_add_f32_e32 v60, v98, v99
	v_add_f32_e32 v56, v102, v103
	v_add_f32_e32 v58, v106, v58
	v_add_f32_e32 v59, v59, v60
	v_add_f32_e32 v56, 0, v56
	v_add_f32_e32 v58, v58, v59
	v_add_f32_e32 v56, v58, v56
	v_mul_f32_e32 v58, v53, v53
	v_mul_f32_e32 v59, v55, v55
	v_fmac_f32_e32 v58, v52, v52
	v_fmac_f32_e32 v59, v54, v54
	v_add_f32_e32 v58, v58, v59
	v_mul_f32_e32 v59, v101, v101
	v_mul_f32_e32 v60, v99, v99
	v_fmac_f32_e32 v59, v100, v100
	v_fmac_f32_e32 v60, v98, v98
	v_add_f32_e32 v59, v59, v60
	v_add_f32_e32 v58, v58, v59
	v_add_f32_e32 v57, v57, v58
	ds_bpermute_b32 v59, v198, v56
	ds_bpermute_b32 v58, v198, v57
	global_store_dwordx4 v[108:109], v[48:51], off
	v_cvt_pk_bf16_f32 v52, v52, v53
	v_cvt_pk_bf16_f32 v53, v54, v55
	s_waitcnt lgkmcnt(1)
	v_add_f32_e32 v48, v56, v59
	s_waitcnt lgkmcnt(0)
	v_add_f32_e32 v50, v57, v58
	ds_bpermute_b32 v49, v179, v48
	ds_bpermute_b32 v51, v179, v50
	v_cvt_pk_bf16_f32 v54, v100, v101
	v_cvt_pk_bf16_f32 v55, v98, v99
	global_store_dwordx4 v[108:109], v[52:55], off offset:256
	s_and_saveexec_b64 s[34:35], s[2:3]
	s_cbranch_execz .LBB0_1025
	v_lshl_add_u64 v[52:53], v[96:97], 2, s[8:9]
	s_waitcnt lgkmcnt(1)
	v_add_f32_e32 v48, v48, v49
	s_waitcnt lgkmcnt(0)
	v_add_f32_e32 v49, v50, v51
	v_mov_b32_e32 v231, v48
	v_mov_b32_e32 v232, v49
; __device__ __forceinline__ unsigned pk2(float lo, float hi) { f32x2v v = {lo, hi}; b16x2v b = __builtin_convertvector(v, b16x2v); return __builtin_bit_cast(unsigned, b); }
; __device__ __forceinline__ float bflo(unsigned v) { return __uint_as_float(v << 16); }
; __device__ __forceinline__ float bfhi(unsigned v) { return __uint_as_float(v & 0xffff0000u); }
;     __device__ __forceinline__ void operator()(const f32x4 (&acc)[2][2][4][2], const Unit& u, int wr, int wc, int fr, int fq) const {
;     ...
;             for (int m = 0; m < 4; ++m) {
;                 const int row = u.pm * 256 + ai * 128 + wr * 64 + m * 16 + fr;
;                 float mu = 0.f, rs = 1.f;
;                 if (MODE == 1) { const f32x2v s2 = *(const f32x2v*)(stp + 2 * row); mu = s2.x * (1.0f / DM); rs = rsqrtf(fmaxf(s2.y * (1.0f / DM) - mu * mu, 0.f) + LN_EPS); }
;                 const bf16_t* xrow = xb + (size_t)row * DM + colb; bf16_t* orow = Rb + (size_t)row * DM + colb;
;                 float sum = 0.f, sq = 0.f;
; #pragma unroll
;                 for (int bj = 0; bj < 2; ++bj) {
;                     const u32x4 xw = *(const u32x4*)(xrow + 128 * bj);
;                     f32x4 x0 = {bflo(xw.x), bfhi(xw.x), bflo(xw.y), bfhi(xw.y)}, x1 = {bflo(xw.z), bfhi(xw.z), bflo(xw.w), bfhi(xw.w)};
;                     if (MODE == 1) { x0 = (x0 - mu) * rs * g4[bj][0] + b4[bj][0]; x1 = (x1 - mu) * rs * g4[bj][1] + b4[bj][1]; }
;                     const f32x4 r0 = x0 * DN_ALPHA + acc[ai][bj][m][0], r1 = x1 * DN_ALPHA + acc[ai][bj][m][1];
;                     u32x4 w; w.x = pk2(r0[0], r0[1]); w.y = pk2(r0[2], r0[3]); w.z = pk2(r1[0], r1[1]); w.w = pk2(r1[2], r1[3]);
;                     *(u32x4*)(orow + 128 * bj) = w;
;                     sum += ((r0[0] + r0[1]) + (r0[2] + r0[3])) + ((r1[0] + r1[1]) + (r1[2] + r1[3]));
;                     sq += ((r0[0] * r0[0] + r0[1] * r0[1]) + (r0[2] * r0[2] + r0[3] * r0[3])) + ((r1[0] * r1[0] + r1[1] * r1[1]) + (r1[2] * r1[2] + r1[3] * r1[3]));
;                 }
;                 sum += __shfl_xor(sum, 16); sum += __shfl_xor(sum, 32); sq += __shfl_xor(sq, 16); sq += __shfl_xor(sq, 32);
;                 if (fq == 0) { atomicAdd(st + 2 * row, sum); atomicAdd(st + 2 * row + 1, sq); }
.LBB0_1025:
	s_or_b64 exec, exec, s[34:35]
	v_add_u32_e32 v50, 0x90, v178
	v_lshlrev_b32_e32 v48, 1, v50
	s_waitcnt lgkmcnt(1)
	v_ashrrev_i32_e32 v49, 31, v48
	v_lshl_add_u64 v[52:53], v[48:49], 2, s[58:59]
	global_load_dwordx2 v[58:59], v[52:53], off
	s_waitcnt lgkmcnt(0)
	v_ashrrev_i32_e32 v51, 31, v50
	v_lshlrev_b64 v[60:61], 11, v[50:51]
	v_lshl_add_u64 v[50:51], s[0:1], 0, v[60:61]
	v_lshl_add_u64 v[54:55], v[50:51], 0, v[176:177]
	global_load_dwordx4 v[50:53], v[54:55], off
	s_nop 0
	global_load_dwordx4 v[54:57], v[54:55], off offset:256
	v_lshl_add_u64 v[60:61], s[6:7], 0, v[60:61]
	v_lshl_add_u64 v[60:61], v[60:61], 0, v[176:177]
	s_waitcnt vmcnt(2)
	v_pk_mul_f32 v[58:59], v[58:59], s[20:21] op_sel_hi:[1,0]
	s_nop 0
	v_fma_f32 v59, -v58, v58, v59
	v_max_f32_e32 v59, 0, v59
	v_add_f32_e32 v59, 0x3727c5ac, v59
	s_waitcnt vmcnt(1)
	v_and_b32_e32 v98, 0xffff0000, v52
	s_waitcnt vmcnt(0)
	v_lshlrev_b32_e32 v103, 16, v55
	v_and_b32_e32 v104, 0xffff0000, v55
	v_sub_f32_e32 v55, v98, v58
	v_mul_f32_e32 v98, 0x4b800000, v59
	v_cmp_gt_f32_e32 vcc, s65, v59
	v_and_b32_e32 v100, 0xffff0000, v53
	v_lshlrev_b32_e32 v107, 16, v57
	v_cndmask_b32_e32 v59, v59, v98, vcc
	v_and_b32_e32 v108, 0xffff0000, v57
	v_sub_f32_e32 v57, v100, v58
	v_rsq_f32_e32 v100, v59
	v_lshlrev_b32_e32 v62, 16, v50
	v_and_b32_e32 v50, 0xffff0000, v50
	v_lshlrev_b32_e32 v101, 16, v54
	v_lshlrev_b32_e32 v63, 16, v51
	v_and_b32_e32 v96, 0xffff0000, v51
	v_lshlrev_b32_e32 v97, 16, v52
	v_lshlrev_b32_e32 v99, 16, v53
	v_sub_f32_e32 v51, v50, v58
	v_sub_f32_e32 v50, v62, v58
	v_sub_f32_e32 v62, v101, v58
	v_mul_f32_e32 v101, 0x45800000, v100
	v_and_b32_e32 v102, 0xffff0000, v54
	v_lshlrev_b32_e32 v105, 16, v56
	v_and_b32_e32 v106, 0xffff0000, v56
	v_sub_f32_e32 v53, v96, v58
	v_sub_f32_e32 v52, v63, v58
	v_sub_f32_e32 v54, v97, v58
	v_sub_f32_e32 v56, v99, v58
	v_cndmask_b32_e32 v100, v100, v101, vcc
	v_sub_f32_e32 v63, v102, v58
	v_sub_f32_e32 v97, v104, v58
	v_sub_f32_e32 v96, v103, v58
	v_sub_f32_e32 v99, v106, v58
	v_sub_f32_e32 v98, v105, v58
	v_sub_f32_e32 v59, v108, v58
	v_sub_f32_e32 v58, v107, v58
	v_pk_mul_f32 v[52:53], v[52:53], v[100:101] op_sel_hi:[1,0]
	v_pk_mul_f32 v[50:51], v[50:51], v[100:101] op_sel_hi:[1,0]
	v_pk_mul_f32 v[56:57], v[56:57], v[100:101] op_sel_hi:[1,0]
	v_pk_mul_f32 v[54:55], v[54:55], v[100:101] op_sel_hi:[1,0]
	v_pk_mul_f32 v[58:59], v[58:59], v[100:101] op_sel_hi:[1,0]
	v_pk_mul_f32 v[98:99], v[98:99], v[100:101] op_sel_hi:[1,0]
	v_pk_fma_f32 v[50:51], v[76:77], v[50:51], v[64:65]
	v_pk_fma_f32 v[52:53], v[78:79], v[52:53], v[66:67]
	v_pk_fma_f32 v[54:55], v[68:69], v[54:55], v[72:73]
	v_pk_fma_f32 v[56:57], v[70:71], v[56:57], v[74:75]
	v_pk_fma_f32 v[98:99], v[80:81], v[98:99], v[84:85]
	v_pk_fma_f32 v[58:59], v[82:83], v[58:59], v[86:87]
	v_pk_fma_f32 v[46:47], v[52:53], s[22:23], v[46:47] op_sel_hi:[1,0,1]
	v_pk_fma_f32 v[44:45], v[50:51], s[22:23], v[44:45] op_sel_hi:[1,0,1]
	v_pk_fma_f32 v[42:43], v[56:57], s[22:23], v[42:43] op_sel_hi:[1,0,1]
	v_pk_fma_f32 v[40:41], v[54:55], s[22:23], v[40:41] op_sel_hi:[1,0,1]
	v_pk_mul_f32 v[96:97], v[96:97], v[100:101] op_sel_hi:[1,0]
	v_pk_mul_f32 v[62:63], v[62:63], v[100:101] op_sel_hi:[1,0]
	v_pk_fma_f32 v[50:51], v[58:59], s[22:23], v[34:35] op_sel_hi:[1,0,1]
	v_pk_fma_f32 v[52:53], v[98:99], s[22:23], v[32:33] op_sel_hi:[1,0,1]
	v_cvt_pk_bf16_f32 v32, v44, v45
	v_cvt_pk_bf16_f32 v33, v46, v47
	v_cvt_pk_bf16_f32 v34, v40, v41
	v_cvt_pk_bf16_f32 v35, v42, v43
	v_add_f32_e32 v54, v44, v45
	v_add_f32_e32 v55, v46, v47
	v_add_f32_e32 v56, v40, v41
	v_add_f32_e32 v57, v42, v43
	v_mul_f32_e32 v45, v45, v45
	v_mul_f32_e32 v47, v47, v47
	v_mul_f32_e32 v41, v41, v41
	v_mul_f32_e32 v43, v43, v43
	v_pk_fma_f32 v[62:63], v[88:89], v[62:63], v[92:93]
	v_pk_fma_f32 v[96:97], v[90:91], v[96:97], v[94:95]
	v_fmac_f32_e32 v45, v44, v44
	v_fmac_f32_e32 v47, v46, v46
	v_fmac_f32_e32 v41, v40, v40
	v_fmac_f32_e32 v43, v42, v42
	v_pk_fma_f32 v[38:39], v[96:97], s[22:23], v[38:39] op_sel_hi:[1,0,1]
	v_pk_fma_f32 v[36:37], v[62:63], s[22:23], v[36:37] op_sel_hi:[1,0,1]
	v_add_f32_e32 v42, v45, v47
	v_add_f32_e32 v41, v41, v43
	v_add_f32_e32 v58, v36, v37
	v_add_f32_e32 v54, v54, v55
	v_add_f32_e32 v55, v56, v57
	v_add_f32_e32 v41, v42, v41
	v_add_f32_e32 v42, v38, v39
	v_add_f32_e32 v43, v52, v53
	v_add_f32_e32 v44, v50, v51
	v_add_f32_e32 v40, v54, v55
	v_add_f32_e32 v42, v58, v42
	v_add_f32_e32 v43, v43, v44
	v_add_f32_e32 v40, 0, v40
	v_add_f32_e32 v42, v42, v43
	v_add_f32_e32 v40, v42, v40
	v_mul_f32_e32 v42, v37, v37
	v_mul_f32_e32 v43, v39, v39
	v_fmac_f32_e32 v42, v36, v36
	v_fmac_f32_e32 v43, v38, v38
	v_add_f32_e32 v42, v42, v43
	v_mul_f32_e32 v43, v53, v53
	v_mul_f32_e32 v44, v51, v51
	v_fmac_f32_e32 v43, v52, v52
	v_fmac_f32_e32 v44, v50, v50
	v_add_f32_e32 v43, v43, v44
	v_add_f32_e32 v42, v42, v43
	v_add_f32_e32 v41, v41, v42
	ds_bpermute_b32 v43, v198, v40
	ds_bpermute_b32 v42, v198, v41
	global_store_dwordx4 v[60:61], v[32:35], off
	v_cvt_pk_bf16_f32 v36, v36, v37
	v_cvt_pk_bf16_f32 v37, v38, v39
	s_waitcnt lgkmcnt(1)
	v_add_f32_e32 v32, v40, v43
	s_waitcnt lgkmcnt(0)
	v_add_f32_e32 v34, v41, v42
	ds_bpermute_b32 v33, v179, v32
	ds_bpermute_b32 v35, v179, v34
	v_cvt_pk_bf16_f32 v38, v52, v53
	v_cvt_pk_bf16_f32 v39, v50, v51
	global_store_dwordx4 v[60:61], v[36:39], off offset:256
	s_and_saveexec_b64 s[34:35], s[2:3]
	s_cbranch_execz .LBB0_1027
	v_lshl_add_u64 v[36:37], v[48:49], 2, s[8:9]
	s_waitcnt lgkmcnt(1)
	v_add_f32_e32 v32, v32, v33
	s_waitcnt lgkmcnt(0)
	v_add_f32_e32 v33, v34, v35
	v_mov_b32_e32 v233, v32
	v_mov_b32_e32 v234, v33
; __device__ __forceinline__ unsigned pk2(float lo, float hi) { f32x2v v = {lo, hi}; b16x2v b = __builtin_convertvector(v, b16x2v); return __builtin_bit_cast(unsigned, b); }
; __device__ __forceinline__ float bflo(unsigned v) { return __uint_as_float(v << 16); }
; __device__ __forceinline__ float bfhi(unsigned v) { return __uint_as_float(v & 0xffff0000u); }
;     __device__ __forceinline__ void operator()(const f32x4 (&acc)[2][2][4][2], const Unit& u, int wr, int wc, int fr, int fq) const {
;     ...
;             for (int m = 0; m < 4; ++m) {
;                 const int row = u.pm * 256 + ai * 128 + wr * 64 + m * 16 + fr;
;                 float mu = 0.f, rs = 1.f;
;                 if (MODE == 1) { const f32x2v s2 = *(const f32x2v*)(stp + 2 * row); mu = s2.x * (1.0f / DM); rs = rsqrtf(fmaxf(s2.y * (1.0f / DM) - mu * mu, 0.f) + LN_EPS); }
;                 const bf16_t* xrow = xb + (size_t)row * DM + colb; bf16_t* orow = Rb + (size_t)row * DM + colb;
;                 float sum = 0.f, sq = 0.f;
; #pragma unroll
;                 for (int bj = 0; bj < 2; ++bj) {
;                     const u32x4 xw = *(const u32x4*)(xrow + 128 * bj);
;                     f32x4 x0 = {bflo(xw.x), bfhi(xw.x), bflo(xw.y), bfhi(xw.y)}, x1 = {bflo(xw.z), bfhi(xw.z), bflo(xw.w), bfhi(xw.w)};
;                     if (MODE == 1) { x0 = (x0 - mu) * rs * g4[bj][0] + b4[bj][0]; x1 = (x1 - mu) * rs * g4[bj][1] + b4[bj][1]; }
;                     const f32x4 r0 = x0 * DN_ALPHA + acc[ai][bj][m][0], r1 = x1 * DN_ALPHA + acc[ai][bj][m][1];
;                     u32x4 w; w.x = pk2(r0[0], r0[1]); w.y = pk2(r0[2], r0[3]); w.z = pk2(r1[0], r1[1]); w.w = pk2(r1[2], r1[3]);
;                     *(u32x4*)(orow + 128 * bj) = w;
;                     sum += ((r0[0] + r0[1]) + (r0[2] + r0[3])) + ((r1[0] + r1[1]) + (r1[2] + r1[3]));
;                     sq += ((r0[0] * r0[0] + r0[1] * r0[1]) + (r0[2] * r0[2] + r0[3] * r0[3])) + ((r1[0] * r1[0] + r1[1] * r1[1]) + (r1[2] * r1[2] + r1[3] * r1[3]));
;                 }
;                 sum += __shfl_xor(sum, 16); sum += __shfl_xor(sum, 32); sq += __shfl_xor(sq, 16); sq += __shfl_xor(sq, 32);
;                 if (fq == 0) { atomicAdd(st + 2 * row, sum); atomicAdd(st + 2 * row + 1, sq); }
.LBB0_1027:
	s_or_b64 exec, exec, s[34:35]
	v_add_u32_e32 v34, 0xa0, v178
	v_lshlrev_b32_e32 v32, 1, v34
	s_waitcnt lgkmcnt(1)
	v_ashrrev_i32_e32 v33, 31, v32
	v_lshl_add_u64 v[36:37], v[32:33], 2, s[58:59]
	global_load_dwordx2 v[42:43], v[36:37], off
	s_waitcnt lgkmcnt(0)
	v_ashrrev_i32_e32 v35, 31, v34
	v_lshlrev_b64 v[44:45], 11, v[34:35]
	v_lshl_add_u64 v[34:35], s[0:1], 0, v[44:45]
	v_lshl_add_u64 v[38:39], v[34:35], 0, v[176:177]
	global_load_dwordx4 v[34:37], v[38:39], off
	s_nop 0
	global_load_dwordx4 v[38:41], v[38:39], off offset:256
	v_lshl_add_u64 v[44:45], s[6:7], 0, v[44:45]
	v_lshl_add_u64 v[44:45], v[44:45], 0, v[176:177]
	s_waitcnt vmcnt(2)
	v_pk_mul_f32 v[42:43], v[42:43], s[20:21] op_sel_hi:[1,0]
	s_nop 0
	v_fma_f32 v43, -v42, v42, v43
	v_max_f32_e32 v43, 0, v43
	v_add_f32_e32 v43, 0x3727c5ac, v43
	s_waitcnt vmcnt(1)
	v_and_b32_e32 v50, 0xffff0000, v36
	s_waitcnt vmcnt(0)
	v_lshlrev_b32_e32 v55, 16, v39
	v_and_b32_e32 v56, 0xffff0000, v39
	v_sub_f32_e32 v39, v50, v42
	v_mul_f32_e32 v50, 0x4b800000, v43
	v_cmp_gt_f32_e32 vcc, s65, v43
	v_and_b32_e32 v52, 0xffff0000, v37
	v_lshlrev_b32_e32 v59, 16, v41
	v_cndmask_b32_e32 v43, v43, v50, vcc
	v_and_b32_e32 v60, 0xffff0000, v41
	v_sub_f32_e32 v41, v52, v42
	v_rsq_f32_e32 v52, v43
	v_lshlrev_b32_e32 v46, 16, v34
	v_and_b32_e32 v34, 0xffff0000, v34
	v_lshlrev_b32_e32 v53, 16, v38
	v_lshlrev_b32_e32 v47, 16, v35
	v_and_b32_e32 v48, 0xffff0000, v35
	v_lshlrev_b32_e32 v49, 16, v36
	v_lshlrev_b32_e32 v51, 16, v37
	v_sub_f32_e32 v35, v34, v42
	v_sub_f32_e32 v34, v46, v42
	v_sub_f32_e32 v46, v53, v42
	v_mul_f32_e32 v53, 0x45800000, v52
	v_and_b32_e32 v54, 0xffff0000, v38
	v_lshlrev_b32_e32 v57, 16, v40
	v_and_b32_e32 v58, 0xffff0000, v40
	v_sub_f32_e32 v37, v48, v42
	v_sub_f32_e32 v36, v47, v42
	v_sub_f32_e32 v38, v49, v42
	v_sub_f32_e32 v40, v51, v42
	v_cndmask_b32_e32 v52, v52, v53, vcc
	v_sub_f32_e32 v47, v54, v42
	v_sub_f32_e32 v49, v56, v42
	v_sub_f32_e32 v48, v55, v42
	v_sub_f32_e32 v51, v58, v42
	v_sub_f32_e32 v50, v57, v42
	v_sub_f32_e32 v43, v60, v42
	v_sub_f32_e32 v42, v59, v42
	v_pk_mul_f32 v[36:37], v[36:37], v[52:53] op_sel_hi:[1,0]
	v_pk_mul_f32 v[34:35], v[34:35], v[52:53] op_sel_hi:[1,0]
	v_pk_mul_f32 v[40:41], v[40:41], v[52:53] op_sel_hi:[1,0]
	v_pk_mul_f32 v[38:39], v[38:39], v[52:53] op_sel_hi:[1,0]
	v_pk_mul_f32 v[42:43], v[42:43], v[52:53] op_sel_hi:[1,0]
	v_pk_mul_f32 v[50:51], v[50:51], v[52:53] op_sel_hi:[1,0]
	v_pk_fma_f32 v[34:35], v[76:77], v[34:35], v[64:65]
	v_pk_fma_f32 v[36:37], v[78:79], v[36:37], v[66:67]
	v_pk_fma_f32 v[38:39], v[68:69], v[38:39], v[72:73]
	v_pk_fma_f32 v[40:41], v[70:71], v[40:41], v[74:75]
	v_pk_fma_f32 v[50:51], v[80:81], v[50:51], v[84:85]
	v_pk_fma_f32 v[42:43], v[82:83], v[42:43], v[86:87]
	v_pk_fma_f32 v[30:31], v[36:37], s[22:23], v[30:31] op_sel_hi:[1,0,1]
	v_pk_fma_f32 v[28:29], v[34:35], s[22:23], v[28:29] op_sel_hi:[1,0,1]
	v_pk_fma_f32 v[26:27], v[40:41], s[22:23], v[26:27] op_sel_hi:[1,0,1]
	v_pk_fma_f32 v[24:25], v[38:39], s[22:23], v[24:25] op_sel_hi:[1,0,1]
	v_pk_mul_f32 v[48:49], v[48:49], v[52:53] op_sel_hi:[1,0]
	v_pk_mul_f32 v[46:47], v[46:47], v[52:53] op_sel_hi:[1,0]
	v_pk_fma_f32 v[34:35], v[42:43], s[22:23], v[18:19] op_sel_hi:[1,0,1]
	v_pk_fma_f32 v[36:37], v[50:51], s[22:23], v[16:17] op_sel_hi:[1,0,1]
	v_cvt_pk_bf16_f32 v16, v28, v29
	v_cvt_pk_bf16_f32 v17, v30, v31
	v_cvt_pk_bf16_f32 v18, v24, v25
	v_cvt_pk_bf16_f32 v19, v26, v27
	v_add_f32_e32 v38, v28, v29
	v_add_f32_e32 v39, v30, v31
	v_add_f32_e32 v40, v24, v25
	v_add_f32_e32 v41, v26, v27
	v_mul_f32_e32 v29, v29, v29
	v_mul_f32_e32 v31, v31, v31
	v_mul_f32_e32 v25, v25, v25
	v_mul_f32_e32 v27, v27, v27
	v_pk_fma_f32 v[46:47], v[88:89], v[46:47], v[92:93]
	v_pk_fma_f32 v[48:49], v[90:91], v[48:49], v[94:95]
	v_fmac_f32_e32 v29, v28, v28
	v_fmac_f32_e32 v31, v30, v30
	v_fmac_f32_e32 v25, v24, v24
	v_fmac_f32_e32 v27, v26, v26
	v_pk_fma_f32 v[22:23], v[48:49], s[22:23], v[22:23] op_sel_hi:[1,0,1]
	v_pk_fma_f32 v[20:21], v[46:47], s[22:23], v[20:21] op_sel_hi:[1,0,1]
	v_add_f32_e32 v26, v29, v31
	v_add_f32_e32 v25, v25, v27
	v_add_f32_e32 v42, v20, v21
	v_add_f32_e32 v38, v38, v39
	v_add_f32_e32 v39, v40, v41
	v_add_f32_e32 v25, v26, v25
	v_add_f32_e32 v26, v22, v23
	v_add_f32_e32 v27, v36, v37
	v_add_f32_e32 v28, v34, v35
	v_add_f32_e32 v24, v38, v39
	v_add_f32_e32 v26, v42, v26
	v_add_f32_e32 v27, v27, v28
	v_add_f32_e32 v24, 0, v24
	v_add_f32_e32 v26, v26, v27
	v_add_f32_e32 v24, v26, v24
	v_mul_f32_e32 v26, v21, v21
	v_mul_f32_e32 v27, v23, v23
	v_fmac_f32_e32 v26, v20, v20
	v_fmac_f32_e32 v27, v22, v22
	v_add_f32_e32 v26, v26, v27
	v_mul_f32_e32 v27, v37, v37
	v_mul_f32_e32 v28, v35, v35
	v_fmac_f32_e32 v27, v36, v36
	v_fmac_f32_e32 v28, v34, v34
	v_add_f32_e32 v27, v27, v28
	v_add_f32_e32 v26, v26, v27
	v_add_f32_e32 v25, v25, v26
	ds_bpermute_b32 v27, v198, v24
	ds_bpermute_b32 v26, v198, v25
	global_store_dwordx4 v[44:45], v[16:19], off
	v_cvt_pk_bf16_f32 v20, v20, v21
	v_cvt_pk_bf16_f32 v21, v22, v23
	s_waitcnt lgkmcnt(1)
	v_add_f32_e32 v16, v24, v27
	s_waitcnt lgkmcnt(0)
	v_add_f32_e32 v18, v25, v26
	ds_bpermute_b32 v17, v179, v16
	ds_bpermute_b32 v19, v179, v18
	v_cvt_pk_bf16_f32 v22, v36, v37
	v_cvt_pk_bf16_f32 v23, v34, v35
	global_store_dwordx4 v[44:45], v[20:23], off offset:256
	s_and_saveexec_b64 s[34:35], s[2:3]
	s_cbranch_execz .LBB0_1029
	v_lshl_add_u64 v[20:21], v[32:33], 2, s[8:9]
	s_waitcnt lgkmcnt(1)
	v_add_f32_e32 v16, v16, v17
	s_waitcnt lgkmcnt(0)
	v_add_f32_e32 v17, v18, v19
	v_mov_b32_e32 v235, v16
	v_mov_b32_e32 v236, v17
; __device__ __forceinline__ unsigned pk2(float lo, float hi) { f32x2v v = {lo, hi}; b16x2v b = __builtin_convertvector(v, b16x2v); return __builtin_bit_cast(unsigned, b); }
; __device__ __forceinline__ float bflo(unsigned v) { return __uint_as_float(v << 16); }
; __device__ __forceinline__ float bfhi(unsigned v) { return __uint_as_float(v & 0xffff0000u); }
;     __device__ __forceinline__ void operator()(const f32x4 (&acc)[2][2][4][2], const Unit& u, int wr, int wc, int fr, int fq) const {
;     ...
;             for (int m = 0; m < 4; ++m) {
;                 const int row = u.pm * 256 + ai * 128 + wr * 64 + m * 16 + fr;
;                 float mu = 0.f, rs = 1.f;
;                 if (MODE == 1) { const f32x2v s2 = *(const f32x2v*)(stp + 2 * row); mu = s2.x * (1.0f / DM); rs = rsqrtf(fmaxf(s2.y * (1.0f / DM) - mu * mu, 0.f) + LN_EPS); }
;                 const bf16_t* xrow = xb + (size_t)row * DM + colb; bf16_t* orow = Rb + (size_t)row * DM + colb;
;                 float sum = 0.f, sq = 0.f;
; #pragma unroll
;                 for (int bj = 0; bj < 2; ++bj) {
;                     const u32x4 xw = *(const u32x4*)(xrow + 128 * bj);
;                     f32x4 x0 = {bflo(xw.x), bfhi(xw.x), bflo(xw.y), bfhi(xw.y)}, x1 = {bflo(xw.z), bfhi(xw.z), bflo(xw.w), bfhi(xw.w)};
;                     if (MODE == 1) { x0 = (x0 - mu) * rs * g4[bj][0] + b4[bj][0]; x1 = (x1 - mu) * rs * g4[bj][1] + b4[bj][1]; }
;                     const f32x4 r0 = x0 * DN_ALPHA + acc[ai][bj][m][0], r1 = x1 * DN_ALPHA + acc[ai][bj][m][1];
;                     u32x4 w; w.x = pk2(r0[0], r0[1]); w.y = pk2(r0[2], r0[3]); w.z = pk2(r1[0], r1[1]); w.w = pk2(r1[2], r1[3]);
;                     *(u32x4*)(orow + 128 * bj) = w;
;                     sum += ((r0[0] + r0[1]) + (r0[2] + r0[3])) + ((r1[0] + r1[1]) + (r1[2] + r1[3]));
;                     sq += ((r0[0] * r0[0] + r0[1] * r0[1]) + (r0[2] * r0[2] + r0[3] * r0[3])) + ((r1[0] * r1[0] + r1[1] * r1[1]) + (r1[2] * r1[2] + r1[3] * r1[3]));
;                 }
;                 sum += __shfl_xor(sum, 16); sum += __shfl_xor(sum, 32); sq += __shfl_xor(sq, 16); sq += __shfl_xor(sq, 32);
;                 if (fq == 0) { atomicAdd(st + 2 * row, sum); atomicAdd(st + 2 * row + 1, sq); }
.LBB0_1029:
	s_or_b64 exec, exec, s[34:35]
	v_add_u32_e32 v18, 0xb0, v178
	v_lshlrev_b32_e32 v16, 1, v18
	s_waitcnt lgkmcnt(1)
	v_ashrrev_i32_e32 v17, 31, v16
	v_lshl_add_u64 v[20:21], v[16:17], 2, s[58:59]
	global_load_dwordx2 v[26:27], v[20:21], off
	s_waitcnt lgkmcnt(0)
	v_ashrrev_i32_e32 v19, 31, v18
	v_lshlrev_b64 v[28:29], 11, v[18:19]
	v_lshl_add_u64 v[18:19], s[0:1], 0, v[28:29]
	v_lshl_add_u64 v[22:23], v[18:19], 0, v[176:177]
	global_load_dwordx4 v[18:21], v[22:23], off
	s_nop 0
	global_load_dwordx4 v[22:25], v[22:23], off offset:256
	v_lshl_add_u64 v[28:29], s[6:7], 0, v[28:29]
	v_lshl_add_u64 v[28:29], v[28:29], 0, v[176:177]
	s_waitcnt vmcnt(2)
	v_pk_mul_f32 v[26:27], v[26:27], s[20:21] op_sel_hi:[1,0]
	s_nop 0
	v_fma_f32 v27, -v26, v26, v27
	v_max_f32_e32 v27, 0, v27
	v_add_f32_e32 v27, 0x3727c5ac, v27
	s_waitcnt vmcnt(1)
	v_and_b32_e32 v34, 0xffff0000, v20
	s_waitcnt vmcnt(0)
	v_lshlrev_b32_e32 v39, 16, v23
	v_and_b32_e32 v40, 0xffff0000, v23
	v_sub_f32_e32 v23, v34, v26
	v_mul_f32_e32 v34, 0x4b800000, v27
	v_cmp_gt_f32_e32 vcc, s65, v27
	v_and_b32_e32 v36, 0xffff0000, v21
	v_lshlrev_b32_e32 v43, 16, v25
	v_cndmask_b32_e32 v27, v27, v34, vcc
	v_and_b32_e32 v44, 0xffff0000, v25
	v_sub_f32_e32 v25, v36, v26
	v_rsq_f32_e32 v36, v27
	v_lshlrev_b32_e32 v30, 16, v18
	v_and_b32_e32 v18, 0xffff0000, v18
	v_lshlrev_b32_e32 v37, 16, v22
	v_lshlrev_b32_e32 v31, 16, v19
	v_and_b32_e32 v32, 0xffff0000, v19
	v_lshlrev_b32_e32 v33, 16, v20
	v_lshlrev_b32_e32 v35, 16, v21
	v_sub_f32_e32 v19, v18, v26
	v_sub_f32_e32 v18, v30, v26
	v_sub_f32_e32 v30, v37, v26
	v_mul_f32_e32 v37, 0x45800000, v36
	v_and_b32_e32 v38, 0xffff0000, v22
	v_lshlrev_b32_e32 v41, 16, v24
	v_and_b32_e32 v42, 0xffff0000, v24
	v_sub_f32_e32 v21, v32, v26
	v_sub_f32_e32 v20, v31, v26
	v_sub_f32_e32 v22, v33, v26
	v_sub_f32_e32 v24, v35, v26
	v_cndmask_b32_e32 v36, v36, v37, vcc
	v_sub_f32_e32 v31, v38, v26
	v_sub_f32_e32 v33, v40, v26
	v_sub_f32_e32 v32, v39, v26
	v_sub_f32_e32 v35, v42, v26
	v_sub_f32_e32 v34, v41, v26
	v_sub_f32_e32 v27, v44, v26
	v_sub_f32_e32 v26, v43, v26
	v_pk_mul_f32 v[20:21], v[20:21], v[36:37] op_sel_hi:[1,0]
	v_pk_mul_f32 v[18:19], v[18:19], v[36:37] op_sel_hi:[1,0]
	v_pk_mul_f32 v[24:25], v[24:25], v[36:37] op_sel_hi:[1,0]
	v_pk_mul_f32 v[22:23], v[22:23], v[36:37] op_sel_hi:[1,0]
	v_pk_mul_f32 v[26:27], v[26:27], v[36:37] op_sel_hi:[1,0]
	v_pk_mul_f32 v[34:35], v[34:35], v[36:37] op_sel_hi:[1,0]
	v_pk_fma_f32 v[18:19], v[76:77], v[18:19], v[64:65]
	v_pk_fma_f32 v[20:21], v[78:79], v[20:21], v[66:67]
	v_pk_fma_f32 v[22:23], v[68:69], v[22:23], v[72:73]
	v_pk_fma_f32 v[24:25], v[70:71], v[24:25], v[74:75]
	v_pk_fma_f32 v[34:35], v[80:81], v[34:35], v[84:85]
	v_pk_fma_f32 v[26:27], v[82:83], v[26:27], v[86:87]
	v_pk_fma_f32 v[14:15], v[20:21], s[22:23], v[14:15] op_sel_hi:[1,0,1]
	v_pk_fma_f32 v[12:13], v[18:19], s[22:23], v[12:13] op_sel_hi:[1,0,1]
	v_pk_fma_f32 v[10:11], v[24:25], s[22:23], v[10:11] op_sel_hi:[1,0,1]
	v_pk_fma_f32 v[8:9], v[22:23], s[22:23], v[8:9] op_sel_hi:[1,0,1]
	v_pk_mul_f32 v[32:33], v[32:33], v[36:37] op_sel_hi:[1,0]
	v_pk_mul_f32 v[30:31], v[30:31], v[36:37] op_sel_hi:[1,0]
	v_pk_fma_f32 v[18:19], v[26:27], s[22:23], v[2:3] op_sel_hi:[1,0,1]
	v_pk_fma_f32 v[20:21], v[34:35], s[22:23], v[0:1] op_sel_hi:[1,0,1]
	v_cvt_pk_bf16_f32 v0, v12, v13
	v_cvt_pk_bf16_f32 v1, v14, v15
	v_cvt_pk_bf16_f32 v2, v8, v9
	v_cvt_pk_bf16_f32 v3, v10, v11
	v_add_f32_e32 v22, v12, v13
	v_add_f32_e32 v23, v14, v15
	v_add_f32_e32 v24, v8, v9
	v_add_f32_e32 v25, v10, v11
	v_mul_f32_e32 v13, v13, v13
	v_mul_f32_e32 v15, v15, v15
	v_mul_f32_e32 v9, v9, v9
	v_mul_f32_e32 v11, v11, v11
	v_pk_fma_f32 v[30:31], v[88:89], v[30:31], v[92:93]
	v_pk_fma_f32 v[32:33], v[90:91], v[32:33], v[94:95]
	v_fmac_f32_e32 v13, v12, v12
	v_fmac_f32_e32 v15, v14, v14
	v_fmac_f32_e32 v9, v8, v8
	v_fmac_f32_e32 v11, v10, v10
	v_pk_fma_f32 v[6:7], v[32:33], s[22:23], v[6:7] op_sel_hi:[1,0,1]
	v_pk_fma_f32 v[4:5], v[30:31], s[22:23], v[4:5] op_sel_hi:[1,0,1]
	v_add_f32_e32 v10, v13, v15
	v_add_f32_e32 v9, v9, v11
	v_add_f32_e32 v26, v4, v5
	v_add_f32_e32 v22, v22, v23
	v_add_f32_e32 v23, v24, v25
	v_add_f32_e32 v9, v10, v9
	v_add_f32_e32 v10, v6, v7
	v_add_f32_e32 v11, v20, v21
	v_add_f32_e32 v12, v18, v19
	v_add_f32_e32 v8, v22, v23
	v_add_f32_e32 v10, v26, v10
	v_add_f32_e32 v11, v11, v12
	v_add_f32_e32 v8, 0, v8
	v_add_f32_e32 v10, v10, v11
	v_add_f32_e32 v8, v10, v8
	v_mul_f32_e32 v10, v5, v5
	v_mul_f32_e32 v11, v7, v7
	v_fmac_f32_e32 v10, v4, v4
	v_fmac_f32_e32 v11, v6, v6
	v_add_f32_e32 v10, v10, v11
	v_mul_f32_e32 v11, v21, v21
	v_mul_f32_e32 v12, v19, v19
	v_fmac_f32_e32 v11, v20, v20
	v_fmac_f32_e32 v12, v18, v18
	v_add_f32_e32 v11, v11, v12
	v_add_f32_e32 v10, v10, v11
	v_add_f32_e32 v9, v9, v10
	ds_bpermute_b32 v11, v198, v8
	ds_bpermute_b32 v10, v198, v9
	global_store_dwordx4 v[28:29], v[0:3], off
	v_cvt_pk_bf16_f32 v4, v4, v5
	v_cvt_pk_bf16_f32 v5, v6, v7
	s_waitcnt lgkmcnt(1)
	v_add_f32_e32 v0, v8, v11
	s_waitcnt lgkmcnt(0)
	v_add_f32_e32 v2, v9, v10
	ds_bpermute_b32 v1, v179, v0
	ds_bpermute_b32 v3, v179, v2
	v_cvt_pk_bf16_f32 v6, v20, v21
	v_cvt_pk_bf16_f32 v7, v18, v19
	global_store_dwordx4 v[28:29], v[4:7], off offset:256
	s_and_saveexec_b64 s[34:35], s[2:3]
	s_cbranch_execz .LBB0_1031
	v_lshl_add_u64 v[4:5], v[16:17], 2, s[8:9]
	s_waitcnt lgkmcnt(1)
	v_add_f32_e32 v0, v0, v1
	s_waitcnt lgkmcnt(0)
	v_add_f32_e32 v1, v2, v3
	v_mov_b32_e32 v237, v0
	v_mov_b32_e32 v238, v1
.LBB0_1031:
	s_or_b64 exec, exec, s[34:35]
	s_and_saveexec_b64 s[98:99], s[2:3]
	s_cbranch_execz .Ldefat_p6
	v_lshlrev_b32_e32 v240, 1, v178
	v_ashrrev_i32_e32 v241, 31, v240
	v_lshl_add_u64 v[240:241], v[240:241], 2, s[8:9]
	global_atomic_add_f32 v[240:241], v223, off
	global_atomic_add_f32 v[240:241], v224, off offset:4
	global_atomic_add_f32 v[240:241], v225, off offset:128
	global_atomic_add_f32 v[240:241], v226, off offset:132
	global_atomic_add_f32 v[240:241], v227, off offset:256
	global_atomic_add_f32 v[240:241], v228, off offset:260
	global_atomic_add_f32 v[240:241], v229, off offset:384
	global_atomic_add_f32 v[240:241], v230, off offset:388
	global_atomic_add_f32 v[240:241], v231, off offset:1024
	global_atomic_add_f32 v[240:241], v232, off offset:1028
	global_atomic_add_f32 v[240:241], v233, off offset:1152
	global_atomic_add_f32 v[240:241], v234, off offset:1156
	global_atomic_add_f32 v[240:241], v235, off offset:1280
	global_atomic_add_f32 v[240:241], v236, off offset:1284
	global_atomic_add_f32 v[240:241], v237, off offset:1408
	global_atomic_add_f32 v[240:241], v238, off offset:1412
.Ldefat_p6:
	s_or_b64 exec, exec, s[98:99]
	s_andn2_b64 vcc, exec, s[4:5]
	s_mov_b64 s[4:5], -1
	s_cbranch_vccnz .LBB0_1004
	s_andn2_b64 vcc, exec, s[14:15]
	s_cbranch_vccnz .LBB0_1003
	s_barrier
	s_branch .LBB0_1003

; __global__ void __launch_bounds__(512, 2) fwd_megakernel(Args a) {
	.amdhsa_kernel _Z14fwd_megakernel4Args
		.amdhsa_group_segment_fixed_size 0
		.amdhsa_private_segment_fixed_size 0
		.amdhsa_kernarg_size 528
		.amdhsa_user_sgpr_count 2
		.amdhsa_user_sgpr_dispatch_ptr 0
		.amdhsa_user_sgpr_queue_ptr 0
		.amdhsa_user_sgpr_kernarg_segment_ptr 1
		.amdhsa_user_sgpr_dispatch_id 0
		.amdhsa_user_sgpr_kernarg_preload_length 0
		.amdhsa_user_sgpr_kernarg_preload_offset 0
		.amdhsa_user_sgpr_private_segment_size 0
		.amdhsa_uses_dynamic_stack 0
		.amdhsa_enable_private_segment 0
		.amdhsa_system_sgpr_workgroup_id_x 1
		.amdhsa_system_sgpr_workgroup_id_y 0
		.amdhsa_system_sgpr_workgroup_id_z 0
		.amdhsa_system_sgpr_workgroup_info 0
		.amdhsa_system_vgpr_workitem_id 2
		.amdhsa_next_free_vgpr 243
		.amdhsa_next_free_sgpr 102
		.amdhsa_accum_offset 244
		.amdhsa_reserve_vcc 1
		.amdhsa_float_round_mode_32 0
		.amdhsa_float_round_mode_16_64 0
		.amdhsa_float_denorm_mode_32 3
		.amdhsa_float_denorm_mode_16_64 3
		.amdhsa_dx10_clamp 1
		.amdhsa_ieee_mode 1
		.amdhsa_fp16_overflow 0
		.amdhsa_tg_split 0
		.amdhsa_exception_fp_ieee_invalid_op 0
		.amdhsa_exception_fp_denorm_src 0
		.amdhsa_exception_fp_ieee_div_zero 0
		.amdhsa_exception_fp_ieee_overflow 0
		.amdhsa_exception_fp_ieee_underflow 0
		.amdhsa_exception_fp_ieee_inexact 0
		.amdhsa_exception_int_div_zero 0
	.end_amdhsa_kernel

; __global__ void __launch_bounds__(512, 2) fwd_megakernel(Args a) {
amdhsa.kernels:
  - .agpr_count:     0
    .args:
      - .offset:         0
        .size:           272
        .value_kind:     by_value
      - .offset:         272
        .size:           4
        .value_kind:     hidden_block_count_x
      - .offset:         276
        .size:           4
        .value_kind:     hidden_block_count_y
      - .offset:         280
        .size:           4
        .value_kind:     hidden_block_count_z
      - .offset:         284
        .size:           2
        .value_kind:     hidden_group_size_x
      - .offset:         286
        .size:           2
        .value_kind:     hidden_group_size_y
      - .offset:         288
        .size:           2
        .value_kind:     hidden_group_size_z
      - .offset:         290
        .size:           2
        .value_kind:     hidden_remainder_x
      - .offset:         292
        .size:           2
        .value_kind:     hidden_remainder_y
      - .offset:         294
        .size:           2
        .value_kind:     hidden_remainder_z
      - .offset:         312
        .size:           8
        .value_kind:     hidden_global_offset_x
      - .offset:         320
        .size:           8
        .value_kind:     hidden_global_offset_y
      - .offset:         328
        .size:           8
        .value_kind:     hidden_global_offset_z
      - .offset:         336
        .size:           2
        .value_kind:     hidden_grid_dims
      - .offset:         360
        .size:           8
        .value_kind:     hidden_multigrid_sync_arg
      - .offset:         392
        .size:           4
        .value_kind:     hidden_dynamic_lds_size
    .group_segment_fixed_size: 0
    .kernarg_segment_align: 8
    .kernarg_segment_size: 528
    .language:       OpenCL C
    .language_version:
      - 2
      - 0
    .max_flat_workgroup_size: 512
    .name:           _Z14fwd_megakernel4Args
    .private_segment_fixed_size: 0
    .sgpr_count:     108
    .sgpr_spill_count: 52
    .symbol:         _Z14fwd_megakernel4Args.kd
    .uniform_work_group_size: 1
    .uses_dynamic_stack: false
    .vgpr_count:     243
    .vgpr_spill_count: 0
    .wavefront_size: 64
